# v8: P13 conv+silu loop rewritten (packed f32, block-prefetched loads) and q/k/glr staging de-serialised
# baseline (speedup 1.0000x reference)
; #define LAS __attribute__((address_space(3)))
; DI float bflo(unsigned u) { return __uint_as_float(u << 16); }
; DI float bfhi(unsigned u) { return __uint_as_float(u & 0xffff0000u); }
; DI void precompute_item(const Params& p, int item, ldsp lds, int tid_) {
;     ...
;   const bool sample = item >= 256;
;   const int bs = item - 256, c = item & 31;
;   const int r0 = sample ? TP + bs * 4 : (item >> 5) * 2048 + c * 64, ntok = sample ? 4 : 64;
;   ldsp W2L = lds, GL = lds + 16384, QR = lds + 20480, KR = lds + 53248, BT = lds + 86016;
; #pragma unroll
;   for (int i = 0; i < 4; ++i) { const int idx = tid + 512 * i, t = idx >> 5, pc = idx & 31; const bool ok = t < ntok; const bf16_t* sp = proj + (size_t)(r0 + t) * NINP + pc * 8;
;     *(LAS u32x4*)(QR + t * 512 + pc * 16) = ok ? ld16(sp + C_Q) : Z4; *(LAS u32x4*)(KR + t * 512 + pc * 16) = ok ? ld16(sp + C_K) : Z4; }
;   if (tid < 128) { const int t2 = tid >> 1, p2 = tid & 1; const u32x4 rg = (t2 < ntok) ? ld16(proj + (size_t)(r0 + t2) * NINP + C_GLR + p2 * 8) : Z4;
;     *(LAS f32x4*)(GL + (t2 * 16 + p2 * 8) * 4) = (f32x4){bflo(rg.x), bfhi(rg.x), bflo(rg.y), bfhi(rg.y)}; *(LAS f32x4*)(GL + (t2 * 16 + p2 * 8 + 4) * 4) = (f32x4){bflo(rg.z), bfhi(rg.z), bflo(rg.w), bfhi(rg.w)}; }
.LBB0_347:
	s_cmpk_lt_i32 s74, 0x100
	s_cselect_b64 s[4:5], -1, 0
	s_add_i32 s1, s74, 0xffffff00
	s_lshl_b32 s3, s1, 2
	v_mov_b32_e32 v26, v212
	s_add_i32 s6, s3, 0x4000
	s_lshl_b32 s10, s74, 6
	s_cmpk_gt_i32 s74, 0xff
	v_and_b32_e32 v4, 31, v26
	s_cselect_b32 s76, s6, s10
	v_lshlrev_b32_e32 v6, 4, v4
	v_ashrrev_i32_e32 v5, 5, v26
	s_cselect_b32 s3, 4, 64
	v_lshl_add_u64 v[8:9], s[62:63], 0, v[6:7]
	v_add_u32_e32 v0, s76, v5
	v_readfirstlane_b32 s0, v26
	v_cmp_gt_i32_e32 vcc, s3, v5
	v_mad_i64_i32 v[10:11], s[6:7], v0, s85, v[8:9]
	v_lshl_add_u32 v6, v4, 4, 16
	v_lshlrev_b32_e32 v12, 9, v5
	v_add_u32_e32 v12, v6, v12
	v_mov_b32_e32 v40, 0
	v_mov_b32_e32 v41, 0
	v_mov_b32_e32 v42, 0
	v_mov_b32_e32 v43, 0
	v_mov_b32_e32 v44, 0
	v_mov_b32_e32 v45, 0
	v_mov_b32_e32 v46, 0
	v_mov_b32_e32 v47, 0
	v_mov_b32_e32 v48, 0
	v_mov_b32_e32 v49, 0
	v_mov_b32_e32 v50, 0
	v_mov_b32_e32 v51, 0
	v_mov_b32_e32 v52, 0
	v_mov_b32_e32 v53, 0
	v_mov_b32_e32 v54, 0
	v_mov_b32_e32 v55, 0
	v_mov_b32_e32 v56, 0
	v_mov_b32_e32 v57, 0
	v_mov_b32_e32 v58, 0
	v_mov_b32_e32 v59, 0
	v_mov_b32_e32 v60, 0
	v_mov_b32_e32 v61, 0
	v_mov_b32_e32 v62, 0
	v_mov_b32_e32 v63, 0
	v_mov_b32_e32 v64, 0
	v_mov_b32_e32 v65, 0
	v_mov_b32_e32 v66, 0
	v_mov_b32_e32 v67, 0
	v_mov_b32_e32 v68, 0
	v_mov_b32_e32 v69, 0
	v_mov_b32_e32 v70, 0
	v_mov_b32_e32 v71, 0
	v_mov_b32_e32 v72, 0
	v_mov_b32_e32 v73, 0
	v_mov_b32_e32 v74, 0
	v_mov_b32_e32 v75, 0
	v_mov_b32_e32 v16, v5
	v_add_u32_e32 v17, s76, v16
	v_cmp_gt_i32_e32 vcc, s3, v16
	v_mad_i64_i32 v[14:15], s[8:9], v17, s85, v[8:9]
	s_and_saveexec_b64 s[6:7], vcc
	global_load_dwordx4 v[40:43], v[14:15], off
	global_load_dwordx4 v[44:47], v[14:15], off offset:512
	s_or_b64 exec, exec, s[6:7]
	v_add_u32_e32 v16, 16, v5
	v_add_u32_e32 v17, s76, v16
	v_cmp_gt_i32_e32 vcc, s3, v16
	v_mad_i64_i32 v[14:15], s[8:9], v17, s85, v[8:9]
	s_and_saveexec_b64 s[6:7], vcc
	global_load_dwordx4 v[48:51], v[14:15], off
	global_load_dwordx4 v[52:55], v[14:15], off offset:512
	s_or_b64 exec, exec, s[6:7]
	v_add_u32_e32 v16, 32, v5
	v_add_u32_e32 v17, s76, v16
	v_cmp_gt_i32_e32 vcc, s3, v16
	v_mad_i64_i32 v[14:15], s[8:9], v17, s85, v[8:9]
	s_and_saveexec_b64 s[6:7], vcc
	global_load_dwordx4 v[56:59], v[14:15], off
	global_load_dwordx4 v[60:63], v[14:15], off offset:512
	s_or_b64 exec, exec, s[6:7]
	v_add_u32_e32 v16, 48, v5
	v_add_u32_e32 v17, s76, v16
	v_cmp_gt_i32_e32 vcc, s3, v16
	v_mad_i64_i32 v[14:15], s[8:9], v17, s85, v[8:9]
	s_and_saveexec_b64 s[6:7], vcc
	global_load_dwordx4 v[64:67], v[14:15], off
	global_load_dwordx4 v[68:71], v[14:15], off offset:512
	s_or_b64 exec, exec, s[6:7]
	v_ashrrev_i32_e32 v16, 1, v26
	v_and_b32_e32 v17, 1, v26
	v_add_u32_e32 v13, s76, v16
	v_mov_b64_e32 v[14:15], s[62:63]
	v_mad_i64_i32 v[14:15], s[8:9], v13, s85, v[14:15]
	v_lshlrev_b32_e32 v18, 4, v17
	v_mov_b32_e32 v19, 0
	v_lshl_add_u64 v[14:15], v[14:15], 0, v[18:19]
	s_movk_i32 s8, 0x80
	v_cmp_gt_i32_e64 s[12:13], s8, v26
	v_cmp_gt_i32_e32 vcc, s3, v16
	s_and_b64 vcc, vcc, s[12:13]
	s_and_saveexec_b64 s[6:7], vcc
	global_load_dwordx4 v[72:75], v[14:15], off offset:3072
	s_or_b64 exec, exec, s[6:7]
	s_waitcnt vmcnt(0)
	ds_write_b128 v12, v[40:43] offset:20480
	ds_write_b128 v12, v[44:47] offset:53248
	v_add_u32_e32 v13, 0x2000, v12
	ds_write_b128 v13, v[48:51] offset:20480
	ds_write_b128 v13, v[52:55] offset:53248
	v_add_u32_e32 v13, 0x4000, v12
	ds_write_b128 v13, v[56:59] offset:20480
	ds_write_b128 v13, v[60:63] offset:53248
	v_add_u32_e32 v13, 0x6000, v12
	ds_write_b128 v13, v[64:67] offset:20480
	ds_write_b128 v13, v[68:71] offset:53248
	s_and_saveexec_b64 s[6:7], s[12:13]
	v_lshlrev_b32_e32 v76, 16, v72
	v_and_b32_e32 v77, 0xffff0000, v72
	v_lshlrev_b32_e32 v78, 16, v73
	v_and_b32_e32 v79, 0xffff0000, v73
	v_lshlrev_b32_e32 v80, 16, v74
	v_and_b32_e32 v81, 0xffff0000, v74
	v_lshlrev_b32_e32 v82, 16, v75
	v_and_b32_e32 v83, 0xffff0000, v75
	v_lshlrev_b32_e32 v16, 6, v16
	v_lshlrev_b32_e32 v17, 5, v17
	v_add3_u32 v16, 16, v16, v17
	ds_write_b128 v16, v[76:79] offset:16384
	ds_write_b128 v16, v[80:83] offset:16400
	s_or_b64 exec, exec, s[6:7]
	s_mov_b64 s[6:7], exec

; DI unsigned pk2(float lo, float hi) { f32x2 v = {lo, hi}; return __builtin_bit_cast(unsigned, __builtin_convertvector(v, bf16x2v)); }
; DI float bflo(unsigned u) { return __uint_as_float(u << 16); }
; DI float bfhi(unsigned u) { return __uint_as_float(u & 0xffff0000u); }
; DI float siluf(float x) { return x * __builtin_amdgcn_rcpf(1.f + __expf(-x)); }
; DI void precompute_item(const Params& p, int item, ldsp lds, int tid_) {
;     ...
;   {
;     const int ch = 2 * tid;
;     float cw[4][2], cb[2];
; #pragma unroll
;     for (int j = 0; j < 4; ++j) { const f32x2 w = *(const f32x2*)(p.in[14] + j * 1024 + ch); cw[j][0] = w[0]; cw[j][1] = w[1]; }
;     { const f32x2 w = *(const f32x2*)(p.in[15] + ch); cb[0] = w[0]; cb[1] = w[1]; }
;     unsigned x0 = 0u, x1 = 0u, x2 = 0u;
;     if (sample) { const float* sp = p.in[5] + (size_t)bs * 3072 + ch; const f32x2 a0 = *(const f32x2*)sp, a1 = *(const f32x2*)(sp + 1024), a2 = *(const f32x2*)(sp + 2048);
;       x0 = pk2(a0[0], a0[1]); x1 = pk2(a1[0], a1[1]); x2 = pk2(a2[0], a2[1]); }
;     else if (c > 0) { const bf16_t* sp = proj + (size_t)(r0 - 3) * NINP + C_XBC + ch; x0 = *(const unsigned*)sp; x1 = *(const unsigned*)(sp + NINP); x2 = *(const unsigned*)(sp + 2 * NINP); }
;     unsigned* xact = (unsigned*)((bf16_t*)(p.ws + B_XACT) + (size_t)r0 * D + ch);
;     const int nb = sample ? 1 : 4;
; #pragma unroll 1
;     for (int tb = 0; tb < nb; ++tb) {
;       unsigned xr[16];
; #pragma unroll
;       for (int i = 0; i < 16; ++i) { const int t = tb * 16 + i; xr[i] = (t < ntok) ? *(const unsigned*)(proj + (size_t)(r0 + t) * NINP + C_XBC + ch) : 0u; }
; #pragma unroll
;       for (int i = 0; i < 16; ++i) { const int t = tb * 16 + i; const unsigned x3 = xr[i];
;         const float a0 = cb[0] + cw[0][0] * bflo(x0) + cw[1][0] * bflo(x1) + cw[2][0] * bflo(x2) + cw[3][0] * bflo(x3);
;         const float a1 = cb[1] + cw[0][1] * bfhi(x0) + cw[1][1] * bfhi(x1) + cw[2][1] * bfhi(x2) + cw[3][1] * bfhi(x3);
;         if (t < ntok) xact[(size_t)t * (D / 2)] = pk2(siluf(a0), siluf(a1));
;         x0 = x1; x1 = x2; x2 = x3; }
.LBB0_372:
	s_mul_i32 s4, s76, 0x1a00
	s_add_u32 s4, s62, s4
	s_addc_u32 s5, s63, 0
	s_add_u32 s4, s4, 0x1020
	s_addc_u32 s5, s5, 0
	s_lshl_b32 s6, s76, 11
	s_add_u32 s6, s40, s6
	s_addc_u32 s7, s41, 0
	v_lshlrev_b32_e32 v78, 1, v0
	v_mov_b32_e32 v80, 0xbfb8aa3b
	v_mov_b32_e32 v81, 0xbfb8aa3b
	v_mov_b32_e32 v82, 1.0
	v_mov_b32_e32 v83, 1.0
	s_cmp_eq_u32 s3, 64
	s_cbranch_scc0 .Lp13c_small
	global_load_dword v40, v78, s[4:5]
	s_add_u32 s4, s4, 0x1a00
	s_addc_u32 s5, s5, 0
	global_load_dword v41, v78, s[4:5]
	s_add_u32 s4, s4, 0x1a00
	s_addc_u32 s5, s5, 0
	global_load_dword v42, v78, s[4:5]
	s_add_u32 s4, s4, 0x1a00
	s_addc_u32 s5, s5, 0
	global_load_dword v43, v78, s[4:5]
	s_add_u32 s4, s4, 0x1a00
	s_addc_u32 s5, s5, 0
	global_load_dword v44, v78, s[4:5]
	s_add_u32 s4, s4, 0x1a00
	s_addc_u32 s5, s5, 0
	global_load_dword v45, v78, s[4:5]
	s_add_u32 s4, s4, 0x1a00
	s_addc_u32 s5, s5, 0
	global_load_dword v46, v78, s[4:5]
	s_add_u32 s4, s4, 0x1a00
	s_addc_u32 s5, s5, 0
	global_load_dword v47, v78, s[4:5]
	s_add_u32 s4, s4, 0x1a00
	s_addc_u32 s5, s5, 0
	global_load_dword v48, v78, s[4:5]
	s_add_u32 s4, s4, 0x1a00
	s_addc_u32 s5, s5, 0
	global_load_dword v49, v78, s[4:5]
	s_add_u32 s4, s4, 0x1a00
	s_addc_u32 s5, s5, 0
	global_load_dword v50, v78, s[4:5]
	s_add_u32 s4, s4, 0x1a00
	s_addc_u32 s5, s5, 0
	global_load_dword v51, v78, s[4:5]
	s_add_u32 s4, s4, 0x1a00
	s_addc_u32 s5, s5, 0
	global_load_dword v52, v78, s[4:5]
	s_add_u32 s4, s4, 0x1a00
	s_addc_u32 s5, s5, 0
	global_load_dword v53, v78, s[4:5]
	s_add_u32 s4, s4, 0x1a00
	s_addc_u32 s5, s5, 0
	global_load_dword v54, v78, s[4:5]
	s_add_u32 s4, s4, 0x1a00
	s_addc_u32 s5, s5, 0
	global_load_dword v55, v78, s[4:5]
	s_add_u32 s4, s4, 0x1a00
	s_addc_u32 s5, s5, 0
	global_load_dword v56, v78, s[4:5]
	s_add_u32 s4, s4, 0x1a00
	s_addc_u32 s5, s5, 0
	global_load_dword v57, v78, s[4:5]
	s_add_u32 s4, s4, 0x1a00
	s_addc_u32 s5, s5, 0
	global_load_dword v58, v78, s[4:5]
	s_add_u32 s4, s4, 0x1a00
	s_addc_u32 s5, s5, 0
	global_load_dword v59, v78, s[4:5]
	s_add_u32 s4, s4, 0x1a00
	s_addc_u32 s5, s5, 0
	global_load_dword v60, v78, s[4:5]
	s_add_u32 s4, s4, 0x1a00
	s_addc_u32 s5, s5, 0
	global_load_dword v61, v78, s[4:5]
	s_add_u32 s4, s4, 0x1a00
	s_addc_u32 s5, s5, 0
	global_load_dword v62, v78, s[4:5]
	s_add_u32 s4, s4, 0x1a00
	s_addc_u32 s5, s5, 0
	global_load_dword v63, v78, s[4:5]
	s_add_u32 s4, s4, 0x1a00
	s_addc_u32 s5, s5, 0
	global_load_dword v64, v78, s[4:5]
	s_add_u32 s4, s4, 0x1a00
	s_addc_u32 s5, s5, 0
	global_load_dword v65, v78, s[4:5]
	s_add_u32 s4, s4, 0x1a00
	s_addc_u32 s5, s5, 0
	global_load_dword v66, v78, s[4:5]
	s_add_u32 s4, s4, 0x1a00
	s_addc_u32 s5, s5, 0
	global_load_dword v67, v78, s[4:5]
	s_add_u32 s4, s4, 0x1a00
	s_addc_u32 s5, s5, 0
	global_load_dword v68, v78, s[4:5]
	s_add_u32 s4, s4, 0x1a00
	s_addc_u32 s5, s5, 0
	global_load_dword v69, v78, s[4:5]
	s_add_u32 s4, s4, 0x1a00
	s_addc_u32 s5, s5, 0
	global_load_dword v70, v78, s[4:5]
	s_add_u32 s4, s4, 0x1a00
	s_addc_u32 s5, s5, 0
	global_load_dword v71, v78, s[4:5]
	s_add_u32 s4, s4, 0x1a00
	s_addc_u32 s5, s5, 0
	s_waitcnt vmcnt(30)
	v_lshlrev_b32_e32 v32, 16, v22
	v_and_b32_e32 v33, 0xffff0000, v22
	v_lshlrev_b32_e32 v34, 16, v21
	v_and_b32_e32 v35, 0xffff0000, v21
	v_lshlrev_b32_e32 v36, 16, v19
	v_and_b32_e32 v37, 0xffff0000, v19
	v_lshlrev_b32_e32 v30, 16, v40
	v_and_b32_e32 v31, 0xffff0000, v40
	v_pk_fma_f32 v[72:73], v[2:3], v[32:33], v[12:13]
	v_pk_fma_f32 v[72:73], v[4:5], v[34:35], v[72:73]
	v_pk_fma_f32 v[72:73], v[8:9], v[36:37], v[72:73]
	v_pk_fma_f32 v[72:73], v[10:11], v[30:31], v[72:73]
	v_lshlrev_b32_e32 v32, 16, v41
	v_and_b32_e32 v33, 0xffff0000, v41
	v_pk_fma_f32 v[74:75], v[2:3], v[34:35], v[12:13]
	v_pk_fma_f32 v[74:75], v[4:5], v[36:37], v[74:75]
	v_pk_fma_f32 v[74:75], v[8:9], v[30:31], v[74:75]
	v_pk_fma_f32 v[74:75], v[10:11], v[32:33], v[74:75]
	v_pk_mul_f32 v[84:85], v[72:73], v[80:81]
	v_pk_mul_f32 v[86:87], v[74:75], v[80:81]
	v_exp_f32_e32 v84, v84
	v_exp_f32_e32 v85, v85
	v_exp_f32_e32 v86, v86
	v_exp_f32_e32 v87, v87
	v_pk_add_f32 v[84:85], v[84:85], v[82:83]
	v_pk_add_f32 v[86:87], v[86:87], v[82:83]
	v_rcp_f32_e32 v84, v84
	v_rcp_f32_e32 v85, v85
	v_rcp_f32_e32 v86, v86
	v_rcp_f32_e32 v87, v87
	v_pk_mul_f32 v[72:73], v[72:73], v[84:85]
	v_pk_mul_f32 v[74:75], v[74:75], v[86:87]
	v_cvt_pk_bf16_f32 v88, v72, v73
	v_cvt_pk_bf16_f32 v89, v74, v75
	global_store_dword v78, v88, s[6:7]
	global_store_dword v78, v89, s[6:7] offset:2048
	s_add_u32 s6, s6, 0x1000
	s_addc_u32 s7, s7, 0
	s_waitcnt vmcnt(30)
	v_lshlrev_b32_e32 v34, 16, v42
	v_and_b32_e32 v35, 0xffff0000, v42
	v_pk_fma_f32 v[72:73], v[2:3], v[36:37], v[12:13]
	v_pk_fma_f32 v[72:73], v[4:5], v[30:31], v[72:73]
	v_pk_fma_f32 v[72:73], v[8:9], v[32:33], v[72:73]
	v_pk_fma_f32 v[72:73], v[10:11], v[34:35], v[72:73]
	v_lshlrev_b32_e32 v36, 16, v43
	v_and_b32_e32 v37, 0xffff0000, v43
	v_pk_fma_f32 v[74:75], v[2:3], v[30:31], v[12:13]
	v_pk_fma_f32 v[74:75], v[4:5], v[32:33], v[74:75]
	v_pk_fma_f32 v[74:75], v[8:9], v[34:35], v[74:75]
	v_pk_fma_f32 v[74:75], v[10:11], v[36:37], v[74:75]
	v_pk_mul_f32 v[84:85], v[72:73], v[80:81]
	v_pk_mul_f32 v[86:87], v[74:75], v[80:81]
	v_exp_f32_e32 v84, v84
	v_exp_f32_e32 v85, v85
	v_exp_f32_e32 v86, v86
	v_exp_f32_e32 v87, v87
	v_pk_add_f32 v[84:85], v[84:85], v[82:83]
	v_pk_add_f32 v[86:87], v[86:87], v[82:83]
	v_rcp_f32_e32 v84, v84
	v_rcp_f32_e32 v85, v85
	v_rcp_f32_e32 v86, v86
	v_rcp_f32_e32 v87, v87
	v_pk_mul_f32 v[72:73], v[72:73], v[84:85]
	v_pk_mul_f32 v[74:75], v[74:75], v[86:87]
	v_cvt_pk_bf16_f32 v88, v72, v73
	v_cvt_pk_bf16_f32 v89, v74, v75
	global_store_dword v78, v88, s[6:7]
	global_store_dword v78, v89, s[6:7] offset:2048
	s_add_u32 s6, s6, 0x1000
	s_addc_u32 s7, s7, 0
	s_waitcnt vmcnt(30)
; DI unsigned pk2(float lo, float hi) { f32x2 v = {lo, hi}; return __builtin_bit_cast(unsigned, __builtin_convertvector(v, bf16x2v)); }
; DI float bflo(unsigned u) { return __uint_as_float(u << 16); }
; DI float bfhi(unsigned u) { return __uint_as_float(u & 0xffff0000u); }
; DI float siluf(float x) { return x * __builtin_amdgcn_rcpf(1.f + __expf(-x)); }
; DI void precompute_item(const Params& p, int item, ldsp lds, int tid_) {
;     ...
;     for (int tb = 0; tb < nb; ++tb) {
;       unsigned xr[16];
; #pragma unroll
;       for (int i = 0; i < 16; ++i) { const int t = tb * 16 + i; xr[i] = (t < ntok) ? *(const unsigned*)(proj + (size_t)(r0 + t) * NINP + C_XBC + ch) : 0u; }
; #pragma unroll
;       for (int i = 0; i < 16; ++i) { const int t = tb * 16 + i; const unsigned x3 = xr[i];
;         const float a0 = cb[0] + cw[0][0] * bflo(x0) + cw[1][0] * bflo(x1) + cw[2][0] * bflo(x2) + cw[3][0] * bflo(x3);
;         const float a1 = cb[1] + cw[0][1] * bfhi(x0) + cw[1][1] * bfhi(x1) + cw[2][1] * bfhi(x2) + cw[3][1] * bfhi(x3);
;         if (t < ntok) xact[(size_t)t * (D / 2)] = pk2(siluf(a0), siluf(a1));
;         x0 = x1; x1 = x2; x2 = x3; }
	v_lshlrev_b32_e32 v30, 16, v44
	v_and_b32_e32 v31, 0xffff0000, v44
	v_pk_fma_f32 v[72:73], v[2:3], v[32:33], v[12:13]
	v_pk_fma_f32 v[72:73], v[4:5], v[34:35], v[72:73]
	v_pk_fma_f32 v[72:73], v[8:9], v[36:37], v[72:73]
	v_pk_fma_f32 v[72:73], v[10:11], v[30:31], v[72:73]
	v_lshlrev_b32_e32 v32, 16, v45
	v_and_b32_e32 v33, 0xffff0000, v45
	v_pk_fma_f32 v[74:75], v[2:3], v[34:35], v[12:13]
	v_pk_fma_f32 v[74:75], v[4:5], v[36:37], v[74:75]
	v_pk_fma_f32 v[74:75], v[8:9], v[30:31], v[74:75]
	v_pk_fma_f32 v[74:75], v[10:11], v[32:33], v[74:75]
	v_pk_mul_f32 v[84:85], v[72:73], v[80:81]
	v_pk_mul_f32 v[86:87], v[74:75], v[80:81]
	v_exp_f32_e32 v84, v84
	v_exp_f32_e32 v85, v85
	v_exp_f32_e32 v86, v86
	v_exp_f32_e32 v87, v87
	v_pk_add_f32 v[84:85], v[84:85], v[82:83]
	v_pk_add_f32 v[86:87], v[86:87], v[82:83]
	v_rcp_f32_e32 v84, v84
	v_rcp_f32_e32 v85, v85
	v_rcp_f32_e32 v86, v86
	v_rcp_f32_e32 v87, v87
	v_pk_mul_f32 v[72:73], v[72:73], v[84:85]
	v_pk_mul_f32 v[74:75], v[74:75], v[86:87]
	v_cvt_pk_bf16_f32 v88, v72, v73
	v_cvt_pk_bf16_f32 v89, v74, v75
	global_store_dword v78, v88, s[6:7]
	global_store_dword v78, v89, s[6:7] offset:2048
	s_add_u32 s6, s6, 0x1000
	s_addc_u32 s7, s7, 0
	s_waitcnt vmcnt(30)
	v_lshlrev_b32_e32 v34, 16, v46
	v_and_b32_e32 v35, 0xffff0000, v46
	v_pk_fma_f32 v[72:73], v[2:3], v[36:37], v[12:13]
	v_pk_fma_f32 v[72:73], v[4:5], v[30:31], v[72:73]
	v_pk_fma_f32 v[72:73], v[8:9], v[32:33], v[72:73]
	v_pk_fma_f32 v[72:73], v[10:11], v[34:35], v[72:73]
	v_lshlrev_b32_e32 v36, 16, v47
	v_and_b32_e32 v37, 0xffff0000, v47
	v_pk_fma_f32 v[74:75], v[2:3], v[30:31], v[12:13]
	v_pk_fma_f32 v[74:75], v[4:5], v[32:33], v[74:75]
	v_pk_fma_f32 v[74:75], v[8:9], v[34:35], v[74:75]
	v_pk_fma_f32 v[74:75], v[10:11], v[36:37], v[74:75]
	v_pk_mul_f32 v[84:85], v[72:73], v[80:81]
	v_pk_mul_f32 v[86:87], v[74:75], v[80:81]
	v_exp_f32_e32 v84, v84
	v_exp_f32_e32 v85, v85
	v_exp_f32_e32 v86, v86
	v_exp_f32_e32 v87, v87
	v_pk_add_f32 v[84:85], v[84:85], v[82:83]
	v_pk_add_f32 v[86:87], v[86:87], v[82:83]
	v_rcp_f32_e32 v84, v84
	v_rcp_f32_e32 v85, v85
	v_rcp_f32_e32 v86, v86
	v_rcp_f32_e32 v87, v87
	v_pk_mul_f32 v[72:73], v[72:73], v[84:85]
	v_pk_mul_f32 v[74:75], v[74:75], v[86:87]
	v_cvt_pk_bf16_f32 v88, v72, v73
	v_cvt_pk_bf16_f32 v89, v74, v75
	global_store_dword v78, v88, s[6:7]
	global_store_dword v78, v89, s[6:7] offset:2048
	s_add_u32 s6, s6, 0x1000
	s_addc_u32 s7, s7, 0
	s_waitcnt vmcnt(30)
	v_lshlrev_b32_e32 v30, 16, v48
	v_and_b32_e32 v31, 0xffff0000, v48
	v_pk_fma_f32 v[72:73], v[2:3], v[32:33], v[12:13]
	v_pk_fma_f32 v[72:73], v[4:5], v[34:35], v[72:73]
	v_pk_fma_f32 v[72:73], v[8:9], v[36:37], v[72:73]
	v_pk_fma_f32 v[72:73], v[10:11], v[30:31], v[72:73]
	v_lshlrev_b32_e32 v32, 16, v49
	v_and_b32_e32 v33, 0xffff0000, v49
	v_pk_fma_f32 v[74:75], v[2:3], v[34:35], v[12:13]
	v_pk_fma_f32 v[74:75], v[4:5], v[36:37], v[74:75]
	v_pk_fma_f32 v[74:75], v[8:9], v[30:31], v[74:75]
	v_pk_fma_f32 v[74:75], v[10:11], v[32:33], v[74:75]
	v_pk_mul_f32 v[84:85], v[72:73], v[80:81]
	v_pk_mul_f32 v[86:87], v[74:75], v[80:81]
	v_exp_f32_e32 v84, v84
	v_exp_f32_e32 v85, v85
	v_exp_f32_e32 v86, v86
	v_exp_f32_e32 v87, v87
	v_pk_add_f32 v[84:85], v[84:85], v[82:83]
	v_pk_add_f32 v[86:87], v[86:87], v[82:83]
	v_rcp_f32_e32 v84, v84
	v_rcp_f32_e32 v85, v85
	v_rcp_f32_e32 v86, v86
	v_rcp_f32_e32 v87, v87
	v_pk_mul_f32 v[72:73], v[72:73], v[84:85]
	v_pk_mul_f32 v[74:75], v[74:75], v[86:87]
	v_cvt_pk_bf16_f32 v88, v72, v73
	v_cvt_pk_bf16_f32 v89, v74, v75
	global_store_dword v78, v88, s[6:7]
	global_store_dword v78, v89, s[6:7] offset:2048
	s_add_u32 s6, s6, 0x1000
	s_addc_u32 s7, s7, 0
	s_waitcnt vmcnt(30)
	v_lshlrev_b32_e32 v34, 16, v50
	v_and_b32_e32 v35, 0xffff0000, v50
	v_pk_fma_f32 v[72:73], v[2:3], v[36:37], v[12:13]
	v_pk_fma_f32 v[72:73], v[4:5], v[30:31], v[72:73]
	v_pk_fma_f32 v[72:73], v[8:9], v[32:33], v[72:73]
	v_pk_fma_f32 v[72:73], v[10:11], v[34:35], v[72:73]
	v_lshlrev_b32_e32 v36, 16, v51
	v_and_b32_e32 v37, 0xffff0000, v51
	v_pk_fma_f32 v[74:75], v[2:3], v[30:31], v[12:13]
	v_pk_fma_f32 v[74:75], v[4:5], v[32:33], v[74:75]
	v_pk_fma_f32 v[74:75], v[8:9], v[34:35], v[74:75]
	v_pk_fma_f32 v[74:75], v[10:11], v[36:37], v[74:75]
	v_pk_mul_f32 v[84:85], v[72:73], v[80:81]
	v_pk_mul_f32 v[86:87], v[74:75], v[80:81]
	v_exp_f32_e32 v84, v84
	v_exp_f32_e32 v85, v85
	v_exp_f32_e32 v86, v86
	v_exp_f32_e32 v87, v87
	v_pk_add_f32 v[84:85], v[84:85], v[82:83]
	v_pk_add_f32 v[86:87], v[86:87], v[82:83]
	v_rcp_f32_e32 v84, v84
	v_rcp_f32_e32 v85, v85
	v_rcp_f32_e32 v86, v86
	v_rcp_f32_e32 v87, v87
	v_pk_mul_f32 v[72:73], v[72:73], v[84:85]
	v_pk_mul_f32 v[74:75], v[74:75], v[86:87]
	v_cvt_pk_bf16_f32 v88, v72, v73
	v_cvt_pk_bf16_f32 v89, v74, v75
	global_store_dword v78, v88, s[6:7]
	global_store_dword v78, v89, s[6:7] offset:2048
	s_add_u32 s6, s6, 0x1000
	s_addc_u32 s7, s7, 0
	s_waitcnt vmcnt(30)
	v_lshlrev_b32_e32 v30, 16, v52
	v_and_b32_e32 v31, 0xffff0000, v52
	v_pk_fma_f32 v[72:73], v[2:3], v[32:33], v[12:13]
	v_pk_fma_f32 v[72:73], v[4:5], v[34:35], v[72:73]
	v_pk_fma_f32 v[72:73], v[8:9], v[36:37], v[72:73]
	v_pk_fma_f32 v[72:73], v[10:11], v[30:31], v[72:73]
	v_lshlrev_b32_e32 v32, 16, v53
	v_and_b32_e32 v33, 0xffff0000, v53
	v_pk_fma_f32 v[74:75], v[2:3], v[34:35], v[12:13]
	v_pk_fma_f32 v[74:75], v[4:5], v[36:37], v[74:75]
	v_pk_fma_f32 v[74:75], v[8:9], v[30:31], v[74:75]
	v_pk_fma_f32 v[74:75], v[10:11], v[32:33], v[74:75]
	v_pk_mul_f32 v[84:85], v[72:73], v[80:81]
	v_pk_mul_f32 v[86:87], v[74:75], v[80:81]
	v_exp_f32_e32 v84, v84
	v_exp_f32_e32 v85, v85
	v_exp_f32_e32 v86, v86
	v_exp_f32_e32 v87, v87
	v_pk_add_f32 v[84:85], v[84:85], v[82:83]
	v_pk_add_f32 v[86:87], v[86:87], v[82:83]
	v_rcp_f32_e32 v84, v84
	v_rcp_f32_e32 v85, v85
	v_rcp_f32_e32 v86, v86
	v_rcp_f32_e32 v87, v87
	v_pk_mul_f32 v[72:73], v[72:73], v[84:85]
	v_pk_mul_f32 v[74:75], v[74:75], v[86:87]
	v_cvt_pk_bf16_f32 v88, v72, v73
	v_cvt_pk_bf16_f32 v89, v74, v75
	global_store_dword v78, v88, s[6:7]
	global_store_dword v78, v89, s[6:7] offset:2048
	s_add_u32 s6, s6, 0x1000
	s_addc_u32 s7, s7, 0
	s_waitcnt vmcnt(30)
; DI unsigned pk2(float lo, float hi) { f32x2 v = {lo, hi}; return __builtin_bit_cast(unsigned, __builtin_convertvector(v, bf16x2v)); }
; DI float bflo(unsigned u) { return __uint_as_float(u << 16); }
; DI float bfhi(unsigned u) { return __uint_as_float(u & 0xffff0000u); }
; DI float siluf(float x) { return x * __builtin_amdgcn_rcpf(1.f + __expf(-x)); }
; DI void precompute_item(const Params& p, int item, ldsp lds, int tid_) {
;     ...
;     for (int tb = 0; tb < nb; ++tb) {
;       unsigned xr[16];
; #pragma unroll
;       for (int i = 0; i < 16; ++i) { const int t = tb * 16 + i; xr[i] = (t < ntok) ? *(const unsigned*)(proj + (size_t)(r0 + t) * NINP + C_XBC + ch) : 0u; }
; #pragma unroll
;       for (int i = 0; i < 16; ++i) { const int t = tb * 16 + i; const unsigned x3 = xr[i];
;         const float a0 = cb[0] + cw[0][0] * bflo(x0) + cw[1][0] * bflo(x1) + cw[2][0] * bflo(x2) + cw[3][0] * bflo(x3);
;         const float a1 = cb[1] + cw[0][1] * bfhi(x0) + cw[1][1] * bfhi(x1) + cw[2][1] * bfhi(x2) + cw[3][1] * bfhi(x3);
;         if (t < ntok) xact[(size_t)t * (D / 2)] = pk2(siluf(a0), siluf(a1));
;         x0 = x1; x1 = x2; x2 = x3; }
	v_lshlrev_b32_e32 v34, 16, v54
	v_and_b32_e32 v35, 0xffff0000, v54
	v_pk_fma_f32 v[72:73], v[2:3], v[36:37], v[12:13]
	v_pk_fma_f32 v[72:73], v[4:5], v[30:31], v[72:73]
	v_pk_fma_f32 v[72:73], v[8:9], v[32:33], v[72:73]
	v_pk_fma_f32 v[72:73], v[10:11], v[34:35], v[72:73]
	v_lshlrev_b32_e32 v36, 16, v55
	v_and_b32_e32 v37, 0xffff0000, v55
	v_pk_fma_f32 v[74:75], v[2:3], v[30:31], v[12:13]
	v_pk_fma_f32 v[74:75], v[4:5], v[32:33], v[74:75]
	v_pk_fma_f32 v[74:75], v[8:9], v[34:35], v[74:75]
	v_pk_fma_f32 v[74:75], v[10:11], v[36:37], v[74:75]
	v_pk_mul_f32 v[84:85], v[72:73], v[80:81]
	v_pk_mul_f32 v[86:87], v[74:75], v[80:81]
	v_exp_f32_e32 v84, v84
	v_exp_f32_e32 v85, v85
	v_exp_f32_e32 v86, v86
	v_exp_f32_e32 v87, v87
	v_pk_add_f32 v[84:85], v[84:85], v[82:83]
	v_pk_add_f32 v[86:87], v[86:87], v[82:83]
	v_rcp_f32_e32 v84, v84
	v_rcp_f32_e32 v85, v85
	v_rcp_f32_e32 v86, v86
	v_rcp_f32_e32 v87, v87
	v_pk_mul_f32 v[72:73], v[72:73], v[84:85]
	v_pk_mul_f32 v[74:75], v[74:75], v[86:87]
	v_cvt_pk_bf16_f32 v88, v72, v73
	v_cvt_pk_bf16_f32 v89, v74, v75
	global_store_dword v78, v88, s[6:7]
	global_store_dword v78, v89, s[6:7] offset:2048
	s_add_u32 s6, s6, 0x1000
	s_addc_u32 s7, s7, 0
	global_load_dword v40, v78, s[4:5]
	s_add_u32 s4, s4, 0x1a00
	s_addc_u32 s5, s5, 0
	global_load_dword v41, v78, s[4:5]
	s_add_u32 s4, s4, 0x1a00
	s_addc_u32 s5, s5, 0
	global_load_dword v42, v78, s[4:5]
	s_add_u32 s4, s4, 0x1a00
	s_addc_u32 s5, s5, 0
	global_load_dword v43, v78, s[4:5]
	s_add_u32 s4, s4, 0x1a00
	s_addc_u32 s5, s5, 0
	global_load_dword v44, v78, s[4:5]
	s_add_u32 s4, s4, 0x1a00
	s_addc_u32 s5, s5, 0
	global_load_dword v45, v78, s[4:5]
	s_add_u32 s4, s4, 0x1a00
	s_addc_u32 s5, s5, 0
	global_load_dword v46, v78, s[4:5]
	s_add_u32 s4, s4, 0x1a00
	s_addc_u32 s5, s5, 0
	global_load_dword v47, v78, s[4:5]
	s_add_u32 s4, s4, 0x1a00
	s_addc_u32 s5, s5, 0
	global_load_dword v48, v78, s[4:5]
	s_add_u32 s4, s4, 0x1a00
	s_addc_u32 s5, s5, 0
	global_load_dword v49, v78, s[4:5]
	s_add_u32 s4, s4, 0x1a00
	s_addc_u32 s5, s5, 0
	global_load_dword v50, v78, s[4:5]
	s_add_u32 s4, s4, 0x1a00
	s_addc_u32 s5, s5, 0
	global_load_dword v51, v78, s[4:5]
	s_add_u32 s4, s4, 0x1a00
	s_addc_u32 s5, s5, 0
	global_load_dword v52, v78, s[4:5]
	s_add_u32 s4, s4, 0x1a00
	s_addc_u32 s5, s5, 0
	global_load_dword v53, v78, s[4:5]
	s_add_u32 s4, s4, 0x1a00
	s_addc_u32 s5, s5, 0
	global_load_dword v54, v78, s[4:5]
	s_add_u32 s4, s4, 0x1a00
	s_addc_u32 s5, s5, 0
	global_load_dword v55, v78, s[4:5]
	s_add_u32 s4, s4, 0x1a00
	s_addc_u32 s5, s5, 0
	s_waitcnt vmcnt(46)
	v_lshlrev_b32_e32 v30, 16, v56
	v_and_b32_e32 v31, 0xffff0000, v56
	v_pk_fma_f32 v[72:73], v[2:3], v[32:33], v[12:13]
	v_pk_fma_f32 v[72:73], v[4:5], v[34:35], v[72:73]
	v_pk_fma_f32 v[72:73], v[8:9], v[36:37], v[72:73]
	v_pk_fma_f32 v[72:73], v[10:11], v[30:31], v[72:73]
	v_lshlrev_b32_e32 v32, 16, v57
	v_and_b32_e32 v33, 0xffff0000, v57
	v_pk_fma_f32 v[74:75], v[2:3], v[34:35], v[12:13]
	v_pk_fma_f32 v[74:75], v[4:5], v[36:37], v[74:75]
	v_pk_fma_f32 v[74:75], v[8:9], v[30:31], v[74:75]
	v_pk_fma_f32 v[74:75], v[10:11], v[32:33], v[74:75]
	v_pk_mul_f32 v[84:85], v[72:73], v[80:81]
	v_pk_mul_f32 v[86:87], v[74:75], v[80:81]
	v_exp_f32_e32 v84, v84
	v_exp_f32_e32 v85, v85
	v_exp_f32_e32 v86, v86
	v_exp_f32_e32 v87, v87
	v_pk_add_f32 v[84:85], v[84:85], v[82:83]
	v_pk_add_f32 v[86:87], v[86:87], v[82:83]
	v_rcp_f32_e32 v84, v84
	v_rcp_f32_e32 v85, v85
	v_rcp_f32_e32 v86, v86
	v_rcp_f32_e32 v87, v87
	v_pk_mul_f32 v[72:73], v[72:73], v[84:85]
	v_pk_mul_f32 v[74:75], v[74:75], v[86:87]
	v_cvt_pk_bf16_f32 v88, v72, v73
	v_cvt_pk_bf16_f32 v89, v74, v75
	global_store_dword v78, v88, s[6:7]
	global_store_dword v78, v89, s[6:7] offset:2048
	s_add_u32 s6, s6, 0x1000
	s_addc_u32 s7, s7, 0
	s_waitcnt vmcnt(46)
	v_lshlrev_b32_e32 v34, 16, v58
	v_and_b32_e32 v35, 0xffff0000, v58
	v_pk_fma_f32 v[72:73], v[2:3], v[36:37], v[12:13]
	v_pk_fma_f32 v[72:73], v[4:5], v[30:31], v[72:73]
	v_pk_fma_f32 v[72:73], v[8:9], v[32:33], v[72:73]
	v_pk_fma_f32 v[72:73], v[10:11], v[34:35], v[72:73]
	v_lshlrev_b32_e32 v36, 16, v59
	v_and_b32_e32 v37, 0xffff0000, v59
	v_pk_fma_f32 v[74:75], v[2:3], v[30:31], v[12:13]
	v_pk_fma_f32 v[74:75], v[4:5], v[32:33], v[74:75]
	v_pk_fma_f32 v[74:75], v[8:9], v[34:35], v[74:75]
	v_pk_fma_f32 v[74:75], v[10:11], v[36:37], v[74:75]
	v_pk_mul_f32 v[84:85], v[72:73], v[80:81]
	v_pk_mul_f32 v[86:87], v[74:75], v[80:81]
	v_exp_f32_e32 v84, v84
	v_exp_f32_e32 v85, v85
	v_exp_f32_e32 v86, v86
	v_exp_f32_e32 v87, v87
	v_pk_add_f32 v[84:85], v[84:85], v[82:83]
	v_pk_add_f32 v[86:87], v[86:87], v[82:83]
	v_rcp_f32_e32 v84, v84
	v_rcp_f32_e32 v85, v85
	v_rcp_f32_e32 v86, v86
	v_rcp_f32_e32 v87, v87
	v_pk_mul_f32 v[72:73], v[72:73], v[84:85]
	v_pk_mul_f32 v[74:75], v[74:75], v[86:87]
	v_cvt_pk_bf16_f32 v88, v72, v73
	v_cvt_pk_bf16_f32 v89, v74, v75
	global_store_dword v78, v88, s[6:7]
	global_store_dword v78, v89, s[6:7] offset:2048
	s_add_u32 s6, s6, 0x1000
	s_addc_u32 s7, s7, 0
	s_waitcnt vmcnt(46)
	v_lshlrev_b32_e32 v30, 16, v60
	v_and_b32_e32 v31, 0xffff0000, v60
	v_pk_fma_f32 v[72:73], v[2:3], v[32:33], v[12:13]
	v_pk_fma_f32 v[72:73], v[4:5], v[34:35], v[72:73]
	v_pk_fma_f32 v[72:73], v[8:9], v[36:37], v[72:73]
	v_pk_fma_f32 v[72:73], v[10:11], v[30:31], v[72:73]
	v_lshlrev_b32_e32 v32, 16, v61
	v_and_b32_e32 v33, 0xffff0000, v61
	v_pk_fma_f32 v[74:75], v[2:3], v[34:35], v[12:13]
	v_pk_fma_f32 v[74:75], v[4:5], v[36:37], v[74:75]
	v_pk_fma_f32 v[74:75], v[8:9], v[30:31], v[74:75]
	v_pk_fma_f32 v[74:75], v[10:11], v[32:33], v[74:75]
	v_pk_mul_f32 v[84:85], v[72:73], v[80:81]
	v_pk_mul_f32 v[86:87], v[74:75], v[80:81]
	v_exp_f32_e32 v84, v84
	v_exp_f32_e32 v85, v85
	v_exp_f32_e32 v86, v86
	v_exp_f32_e32 v87, v87
	v_pk_add_f32 v[84:85], v[84:85], v[82:83]
	v_pk_add_f32 v[86:87], v[86:87], v[82:83]
	v_rcp_f32_e32 v84, v84
	v_rcp_f32_e32 v85, v85
	v_rcp_f32_e32 v86, v86
	v_rcp_f32_e32 v87, v87
	v_pk_mul_f32 v[72:73], v[72:73], v[84:85]
	v_pk_mul_f32 v[74:75], v[74:75], v[86:87]
	v_cvt_pk_bf16_f32 v88, v72, v73
	v_cvt_pk_bf16_f32 v89, v74, v75
	global_store_dword v78, v88, s[6:7]
	global_store_dword v78, v89, s[6:7] offset:2048
	s_add_u32 s6, s6, 0x1000
	s_addc_u32 s7, s7, 0
	s_waitcnt vmcnt(46)
; DI unsigned pk2(float lo, float hi) { f32x2 v = {lo, hi}; return __builtin_bit_cast(unsigned, __builtin_convertvector(v, bf16x2v)); }
; DI float bflo(unsigned u) { return __uint_as_float(u << 16); }
; DI float bfhi(unsigned u) { return __uint_as_float(u & 0xffff0000u); }
; DI float siluf(float x) { return x * __builtin_amdgcn_rcpf(1.f + __expf(-x)); }
; DI void precompute_item(const Params& p, int item, ldsp lds, int tid_) {
;     ...
;     for (int tb = 0; tb < nb; ++tb) {
;       unsigned xr[16];
; #pragma unroll
;       for (int i = 0; i < 16; ++i) { const int t = tb * 16 + i; xr[i] = (t < ntok) ? *(const unsigned*)(proj + (size_t)(r0 + t) * NINP + C_XBC + ch) : 0u; }
; #pragma unroll
;       for (int i = 0; i < 16; ++i) { const int t = tb * 16 + i; const unsigned x3 = xr[i];
;         const float a0 = cb[0] + cw[0][0] * bflo(x0) + cw[1][0] * bflo(x1) + cw[2][0] * bflo(x2) + cw[3][0] * bflo(x3);
;         const float a1 = cb[1] + cw[0][1] * bfhi(x0) + cw[1][1] * bfhi(x1) + cw[2][1] * bfhi(x2) + cw[3][1] * bfhi(x3);
;         if (t < ntok) xact[(size_t)t * (D / 2)] = pk2(siluf(a0), siluf(a1));
;         x0 = x1; x1 = x2; x2 = x3; }
	v_lshlrev_b32_e32 v34, 16, v62
	v_and_b32_e32 v35, 0xffff0000, v62
	v_pk_fma_f32 v[72:73], v[2:3], v[36:37], v[12:13]
	v_pk_fma_f32 v[72:73], v[4:5], v[30:31], v[72:73]
	v_pk_fma_f32 v[72:73], v[8:9], v[32:33], v[72:73]
	v_pk_fma_f32 v[72:73], v[10:11], v[34:35], v[72:73]
	v_lshlrev_b32_e32 v36, 16, v63
	v_and_b32_e32 v37, 0xffff0000, v63
	v_pk_fma_f32 v[74:75], v[2:3], v[30:31], v[12:13]
	v_pk_fma_f32 v[74:75], v[4:5], v[32:33], v[74:75]
	v_pk_fma_f32 v[74:75], v[8:9], v[34:35], v[74:75]
	v_pk_fma_f32 v[74:75], v[10:11], v[36:37], v[74:75]
	v_pk_mul_f32 v[84:85], v[72:73], v[80:81]
	v_pk_mul_f32 v[86:87], v[74:75], v[80:81]
	v_exp_f32_e32 v84, v84
	v_exp_f32_e32 v85, v85
	v_exp_f32_e32 v86, v86
	v_exp_f32_e32 v87, v87
	v_pk_add_f32 v[84:85], v[84:85], v[82:83]
	v_pk_add_f32 v[86:87], v[86:87], v[82:83]
	v_rcp_f32_e32 v84, v84
	v_rcp_f32_e32 v85, v85
	v_rcp_f32_e32 v86, v86
	v_rcp_f32_e32 v87, v87
	v_pk_mul_f32 v[72:73], v[72:73], v[84:85]
	v_pk_mul_f32 v[74:75], v[74:75], v[86:87]
	v_cvt_pk_bf16_f32 v88, v72, v73
	v_cvt_pk_bf16_f32 v89, v74, v75
	global_store_dword v78, v88, s[6:7]
	global_store_dword v78, v89, s[6:7] offset:2048
	s_add_u32 s6, s6, 0x1000
	s_addc_u32 s7, s7, 0
	s_waitcnt vmcnt(46)
	v_lshlrev_b32_e32 v30, 16, v64
	v_and_b32_e32 v31, 0xffff0000, v64
	v_pk_fma_f32 v[72:73], v[2:3], v[32:33], v[12:13]
	v_pk_fma_f32 v[72:73], v[4:5], v[34:35], v[72:73]
	v_pk_fma_f32 v[72:73], v[8:9], v[36:37], v[72:73]
	v_pk_fma_f32 v[72:73], v[10:11], v[30:31], v[72:73]
	v_lshlrev_b32_e32 v32, 16, v65
	v_and_b32_e32 v33, 0xffff0000, v65
	v_pk_fma_f32 v[74:75], v[2:3], v[34:35], v[12:13]
	v_pk_fma_f32 v[74:75], v[4:5], v[36:37], v[74:75]
	v_pk_fma_f32 v[74:75], v[8:9], v[30:31], v[74:75]
	v_pk_fma_f32 v[74:75], v[10:11], v[32:33], v[74:75]
	v_pk_mul_f32 v[84:85], v[72:73], v[80:81]
	v_pk_mul_f32 v[86:87], v[74:75], v[80:81]
	v_exp_f32_e32 v84, v84
	v_exp_f32_e32 v85, v85
	v_exp_f32_e32 v86, v86
	v_exp_f32_e32 v87, v87
	v_pk_add_f32 v[84:85], v[84:85], v[82:83]
	v_pk_add_f32 v[86:87], v[86:87], v[82:83]
	v_rcp_f32_e32 v84, v84
	v_rcp_f32_e32 v85, v85
	v_rcp_f32_e32 v86, v86
	v_rcp_f32_e32 v87, v87
	v_pk_mul_f32 v[72:73], v[72:73], v[84:85]
	v_pk_mul_f32 v[74:75], v[74:75], v[86:87]
	v_cvt_pk_bf16_f32 v88, v72, v73
	v_cvt_pk_bf16_f32 v89, v74, v75
	global_store_dword v78, v88, s[6:7]
	global_store_dword v78, v89, s[6:7] offset:2048
	s_add_u32 s6, s6, 0x1000
	s_addc_u32 s7, s7, 0
	s_waitcnt vmcnt(46)
	v_lshlrev_b32_e32 v34, 16, v66
	v_and_b32_e32 v35, 0xffff0000, v66
	v_pk_fma_f32 v[72:73], v[2:3], v[36:37], v[12:13]
	v_pk_fma_f32 v[72:73], v[4:5], v[30:31], v[72:73]
	v_pk_fma_f32 v[72:73], v[8:9], v[32:33], v[72:73]
	v_pk_fma_f32 v[72:73], v[10:11], v[34:35], v[72:73]
	v_lshlrev_b32_e32 v36, 16, v67
	v_and_b32_e32 v37, 0xffff0000, v67
	v_pk_fma_f32 v[74:75], v[2:3], v[30:31], v[12:13]
	v_pk_fma_f32 v[74:75], v[4:5], v[32:33], v[74:75]
	v_pk_fma_f32 v[74:75], v[8:9], v[34:35], v[74:75]
	v_pk_fma_f32 v[74:75], v[10:11], v[36:37], v[74:75]
	v_pk_mul_f32 v[84:85], v[72:73], v[80:81]
	v_pk_mul_f32 v[86:87], v[74:75], v[80:81]
	v_exp_f32_e32 v84, v84
	v_exp_f32_e32 v85, v85
	v_exp_f32_e32 v86, v86
	v_exp_f32_e32 v87, v87
	v_pk_add_f32 v[84:85], v[84:85], v[82:83]
	v_pk_add_f32 v[86:87], v[86:87], v[82:83]
	v_rcp_f32_e32 v84, v84
	v_rcp_f32_e32 v85, v85
	v_rcp_f32_e32 v86, v86
	v_rcp_f32_e32 v87, v87
	v_pk_mul_f32 v[72:73], v[72:73], v[84:85]
	v_pk_mul_f32 v[74:75], v[74:75], v[86:87]
	v_cvt_pk_bf16_f32 v88, v72, v73
	v_cvt_pk_bf16_f32 v89, v74, v75
	global_store_dword v78, v88, s[6:7]
	global_store_dword v78, v89, s[6:7] offset:2048
	s_add_u32 s6, s6, 0x1000
	s_addc_u32 s7, s7, 0
	s_waitcnt vmcnt(46)
	v_lshlrev_b32_e32 v30, 16, v68
	v_and_b32_e32 v31, 0xffff0000, v68
	v_pk_fma_f32 v[72:73], v[2:3], v[32:33], v[12:13]
	v_pk_fma_f32 v[72:73], v[4:5], v[34:35], v[72:73]
	v_pk_fma_f32 v[72:73], v[8:9], v[36:37], v[72:73]
	v_pk_fma_f32 v[72:73], v[10:11], v[30:31], v[72:73]
	v_lshlrev_b32_e32 v32, 16, v69
	v_and_b32_e32 v33, 0xffff0000, v69
	v_pk_fma_f32 v[74:75], v[2:3], v[34:35], v[12:13]
	v_pk_fma_f32 v[74:75], v[4:5], v[36:37], v[74:75]
	v_pk_fma_f32 v[74:75], v[8:9], v[30:31], v[74:75]
	v_pk_fma_f32 v[74:75], v[10:11], v[32:33], v[74:75]
	v_pk_mul_f32 v[84:85], v[72:73], v[80:81]
	v_pk_mul_f32 v[86:87], v[74:75], v[80:81]
	v_exp_f32_e32 v84, v84
	v_exp_f32_e32 v85, v85
	v_exp_f32_e32 v86, v86
	v_exp_f32_e32 v87, v87
	v_pk_add_f32 v[84:85], v[84:85], v[82:83]
	v_pk_add_f32 v[86:87], v[86:87], v[82:83]
	v_rcp_f32_e32 v84, v84
	v_rcp_f32_e32 v85, v85
	v_rcp_f32_e32 v86, v86
	v_rcp_f32_e32 v87, v87
	v_pk_mul_f32 v[72:73], v[72:73], v[84:85]
	v_pk_mul_f32 v[74:75], v[74:75], v[86:87]
	v_cvt_pk_bf16_f32 v88, v72, v73
	v_cvt_pk_bf16_f32 v89, v74, v75
	global_store_dword v78, v88, s[6:7]
	global_store_dword v78, v89, s[6:7] offset:2048
	s_add_u32 s6, s6, 0x1000
	s_addc_u32 s7, s7, 0
	s_waitcnt vmcnt(46)
; DI unsigned pk2(float lo, float hi) { f32x2 v = {lo, hi}; return __builtin_bit_cast(unsigned, __builtin_convertvector(v, bf16x2v)); }
; DI float bflo(unsigned u) { return __uint_as_float(u << 16); }
; DI float bfhi(unsigned u) { return __uint_as_float(u & 0xffff0000u); }
; DI float siluf(float x) { return x * __builtin_amdgcn_rcpf(1.f + __expf(-x)); }
; DI void precompute_item(const Params& p, int item, ldsp lds, int tid_) {
;     ...
;     for (int tb = 0; tb < nb; ++tb) {
;       unsigned xr[16];
; #pragma unroll
;       for (int i = 0; i < 16; ++i) { const int t = tb * 16 + i; xr[i] = (t < ntok) ? *(const unsigned*)(proj + (size_t)(r0 + t) * NINP + C_XBC + ch) : 0u; }
; #pragma unroll
;       for (int i = 0; i < 16; ++i) { const int t = tb * 16 + i; const unsigned x3 = xr[i];
;         const float a0 = cb[0] + cw[0][0] * bflo(x0) + cw[1][0] * bflo(x1) + cw[2][0] * bflo(x2) + cw[3][0] * bflo(x3);
;         const float a1 = cb[1] + cw[0][1] * bfhi(x0) + cw[1][1] * bfhi(x1) + cw[2][1] * bfhi(x2) + cw[3][1] * bfhi(x3);
;         if (t < ntok) xact[(size_t)t * (D / 2)] = pk2(siluf(a0), siluf(a1));
;         x0 = x1; x1 = x2; x2 = x3; }
	v_lshlrev_b32_e32 v34, 16, v70
	v_and_b32_e32 v35, 0xffff0000, v70
	v_pk_fma_f32 v[72:73], v[2:3], v[36:37], v[12:13]
	v_pk_fma_f32 v[72:73], v[4:5], v[30:31], v[72:73]
	v_pk_fma_f32 v[72:73], v[8:9], v[32:33], v[72:73]
	v_pk_fma_f32 v[72:73], v[10:11], v[34:35], v[72:73]
	v_lshlrev_b32_e32 v36, 16, v71
	v_and_b32_e32 v37, 0xffff0000, v71
	v_pk_fma_f32 v[74:75], v[2:3], v[30:31], v[12:13]
	v_pk_fma_f32 v[74:75], v[4:5], v[32:33], v[74:75]
	v_pk_fma_f32 v[74:75], v[8:9], v[34:35], v[74:75]
	v_pk_fma_f32 v[74:75], v[10:11], v[36:37], v[74:75]
	v_pk_mul_f32 v[84:85], v[72:73], v[80:81]
	v_pk_mul_f32 v[86:87], v[74:75], v[80:81]
	v_exp_f32_e32 v84, v84
	v_exp_f32_e32 v85, v85
	v_exp_f32_e32 v86, v86
	v_exp_f32_e32 v87, v87
	v_pk_add_f32 v[84:85], v[84:85], v[82:83]
	v_pk_add_f32 v[86:87], v[86:87], v[82:83]
	v_rcp_f32_e32 v84, v84
	v_rcp_f32_e32 v85, v85
	v_rcp_f32_e32 v86, v86
	v_rcp_f32_e32 v87, v87
	v_pk_mul_f32 v[72:73], v[72:73], v[84:85]
	v_pk_mul_f32 v[74:75], v[74:75], v[86:87]
	v_cvt_pk_bf16_f32 v88, v72, v73
	v_cvt_pk_bf16_f32 v89, v74, v75
	global_store_dword v78, v88, s[6:7]
	global_store_dword v78, v89, s[6:7] offset:2048
	s_add_u32 s6, s6, 0x1000
	s_addc_u32 s7, s7, 0
	global_load_dword v56, v78, s[4:5]
	s_add_u32 s4, s4, 0x1a00
	s_addc_u32 s5, s5, 0
	global_load_dword v57, v78, s[4:5]
	s_add_u32 s4, s4, 0x1a00
	s_addc_u32 s5, s5, 0
	global_load_dword v58, v78, s[4:5]
	s_add_u32 s4, s4, 0x1a00
	s_addc_u32 s5, s5, 0
	global_load_dword v59, v78, s[4:5]
	s_add_u32 s4, s4, 0x1a00
	s_addc_u32 s5, s5, 0
	global_load_dword v60, v78, s[4:5]
	s_add_u32 s4, s4, 0x1a00
	s_addc_u32 s5, s5, 0
	global_load_dword v61, v78, s[4:5]
	s_add_u32 s4, s4, 0x1a00
	s_addc_u32 s5, s5, 0
	global_load_dword v62, v78, s[4:5]
	s_add_u32 s4, s4, 0x1a00
	s_addc_u32 s5, s5, 0
	global_load_dword v63, v78, s[4:5]
	s_add_u32 s4, s4, 0x1a00
	s_addc_u32 s5, s5, 0
	global_load_dword v64, v78, s[4:5]
	s_add_u32 s4, s4, 0x1a00
	s_addc_u32 s5, s5, 0
	global_load_dword v65, v78, s[4:5]
	s_add_u32 s4, s4, 0x1a00
	s_addc_u32 s5, s5, 0
	global_load_dword v66, v78, s[4:5]
	s_add_u32 s4, s4, 0x1a00
	s_addc_u32 s5, s5, 0
	global_load_dword v67, v78, s[4:5]
	s_add_u32 s4, s4, 0x1a00
	s_addc_u32 s5, s5, 0
	global_load_dword v68, v78, s[4:5]
	s_add_u32 s4, s4, 0x1a00
	s_addc_u32 s5, s5, 0
	global_load_dword v69, v78, s[4:5]
	s_add_u32 s4, s4, 0x1a00
	s_addc_u32 s5, s5, 0
	global_load_dword v70, v78, s[4:5]
	s_add_u32 s4, s4, 0x1a00
	s_addc_u32 s5, s5, 0
	global_load_dword v71, v78, s[4:5]
	s_add_u32 s4, s4, 0x1a00
	s_addc_u32 s5, s5, 0
	s_waitcnt vmcnt(46)
	v_lshlrev_b32_e32 v30, 16, v40
	v_and_b32_e32 v31, 0xffff0000, v40
	v_pk_fma_f32 v[72:73], v[2:3], v[32:33], v[12:13]
	v_pk_fma_f32 v[72:73], v[4:5], v[34:35], v[72:73]
	v_pk_fma_f32 v[72:73], v[8:9], v[36:37], v[72:73]
	v_pk_fma_f32 v[72:73], v[10:11], v[30:31], v[72:73]
	v_lshlrev_b32_e32 v32, 16, v41
	v_and_b32_e32 v33, 0xffff0000, v41
	v_pk_fma_f32 v[74:75], v[2:3], v[34:35], v[12:13]
	v_pk_fma_f32 v[74:75], v[4:5], v[36:37], v[74:75]
	v_pk_fma_f32 v[74:75], v[8:9], v[30:31], v[74:75]
	v_pk_fma_f32 v[74:75], v[10:11], v[32:33], v[74:75]
	v_pk_mul_f32 v[84:85], v[72:73], v[80:81]
	v_pk_mul_f32 v[86:87], v[74:75], v[80:81]
	v_exp_f32_e32 v84, v84
	v_exp_f32_e32 v85, v85
	v_exp_f32_e32 v86, v86
	v_exp_f32_e32 v87, v87
	v_pk_add_f32 v[84:85], v[84:85], v[82:83]
	v_pk_add_f32 v[86:87], v[86:87], v[82:83]
	v_rcp_f32_e32 v84, v84
	v_rcp_f32_e32 v85, v85
	v_rcp_f32_e32 v86, v86
	v_rcp_f32_e32 v87, v87
	v_pk_mul_f32 v[72:73], v[72:73], v[84:85]
	v_pk_mul_f32 v[74:75], v[74:75], v[86:87]
	v_cvt_pk_bf16_f32 v88, v72, v73
	v_cvt_pk_bf16_f32 v89, v74, v75
	global_store_dword v78, v88, s[6:7]
	global_store_dword v78, v89, s[6:7] offset:2048
	s_add_u32 s6, s6, 0x1000
	s_addc_u32 s7, s7, 0
	s_waitcnt vmcnt(46)
	v_lshlrev_b32_e32 v34, 16, v42
	v_and_b32_e32 v35, 0xffff0000, v42
	v_pk_fma_f32 v[72:73], v[2:3], v[36:37], v[12:13]
	v_pk_fma_f32 v[72:73], v[4:5], v[30:31], v[72:73]
	v_pk_fma_f32 v[72:73], v[8:9], v[32:33], v[72:73]
	v_pk_fma_f32 v[72:73], v[10:11], v[34:35], v[72:73]
	v_lshlrev_b32_e32 v36, 16, v43
	v_and_b32_e32 v37, 0xffff0000, v43
	v_pk_fma_f32 v[74:75], v[2:3], v[30:31], v[12:13]
	v_pk_fma_f32 v[74:75], v[4:5], v[32:33], v[74:75]
	v_pk_fma_f32 v[74:75], v[8:9], v[34:35], v[74:75]
	v_pk_fma_f32 v[74:75], v[10:11], v[36:37], v[74:75]
	v_pk_mul_f32 v[84:85], v[72:73], v[80:81]
	v_pk_mul_f32 v[86:87], v[74:75], v[80:81]
	v_exp_f32_e32 v84, v84
	v_exp_f32_e32 v85, v85
	v_exp_f32_e32 v86, v86
	v_exp_f32_e32 v87, v87
	v_pk_add_f32 v[84:85], v[84:85], v[82:83]
	v_pk_add_f32 v[86:87], v[86:87], v[82:83]
	v_rcp_f32_e32 v84, v84
	v_rcp_f32_e32 v85, v85
	v_rcp_f32_e32 v86, v86
	v_rcp_f32_e32 v87, v87
	v_pk_mul_f32 v[72:73], v[72:73], v[84:85]
	v_pk_mul_f32 v[74:75], v[74:75], v[86:87]
	v_cvt_pk_bf16_f32 v88, v72, v73
	v_cvt_pk_bf16_f32 v89, v74, v75
	global_store_dword v78, v88, s[6:7]
	global_store_dword v78, v89, s[6:7] offset:2048
	s_add_u32 s6, s6, 0x1000
	s_addc_u32 s7, s7, 0
	s_waitcnt vmcnt(46)
	v_lshlrev_b32_e32 v30, 16, v44
	v_and_b32_e32 v31, 0xffff0000, v44
	v_pk_fma_f32 v[72:73], v[2:3], v[32:33], v[12:13]
	v_pk_fma_f32 v[72:73], v[4:5], v[34:35], v[72:73]
	v_pk_fma_f32 v[72:73], v[8:9], v[36:37], v[72:73]
	v_pk_fma_f32 v[72:73], v[10:11], v[30:31], v[72:73]
	v_lshlrev_b32_e32 v32, 16, v45
	v_and_b32_e32 v33, 0xffff0000, v45
	v_pk_fma_f32 v[74:75], v[2:3], v[34:35], v[12:13]
	v_pk_fma_f32 v[74:75], v[4:5], v[36:37], v[74:75]
	v_pk_fma_f32 v[74:75], v[8:9], v[30:31], v[74:75]
	v_pk_fma_f32 v[74:75], v[10:11], v[32:33], v[74:75]
	v_pk_mul_f32 v[84:85], v[72:73], v[80:81]
	v_pk_mul_f32 v[86:87], v[74:75], v[80:81]
	v_exp_f32_e32 v84, v84
	v_exp_f32_e32 v85, v85
	v_exp_f32_e32 v86, v86
	v_exp_f32_e32 v87, v87
	v_pk_add_f32 v[84:85], v[84:85], v[82:83]
	v_pk_add_f32 v[86:87], v[86:87], v[82:83]
	v_rcp_f32_e32 v84, v84
	v_rcp_f32_e32 v85, v85
	v_rcp_f32_e32 v86, v86
	v_rcp_f32_e32 v87, v87
	v_pk_mul_f32 v[72:73], v[72:73], v[84:85]
	v_pk_mul_f32 v[74:75], v[74:75], v[86:87]
	v_cvt_pk_bf16_f32 v88, v72, v73
	v_cvt_pk_bf16_f32 v89, v74, v75
	global_store_dword v78, v88, s[6:7]
	global_store_dword v78, v89, s[6:7] offset:2048
	s_add_u32 s6, s6, 0x1000
	s_addc_u32 s7, s7, 0
	s_waitcnt vmcnt(46)
; DI unsigned pk2(float lo, float hi) { f32x2 v = {lo, hi}; return __builtin_bit_cast(unsigned, __builtin_convertvector(v, bf16x2v)); }
; DI float bflo(unsigned u) { return __uint_as_float(u << 16); }
; DI float bfhi(unsigned u) { return __uint_as_float(u & 0xffff0000u); }
; DI float siluf(float x) { return x * __builtin_amdgcn_rcpf(1.f + __expf(-x)); }
; DI void precompute_item(const Params& p, int item, ldsp lds, int tid_) {
;     ...
;     for (int tb = 0; tb < nb; ++tb) {
;       unsigned xr[16];
; #pragma unroll
;       for (int i = 0; i < 16; ++i) { const int t = tb * 16 + i; xr[i] = (t < ntok) ? *(const unsigned*)(proj + (size_t)(r0 + t) * NINP + C_XBC + ch) : 0u; }
; #pragma unroll
;       for (int i = 0; i < 16; ++i) { const int t = tb * 16 + i; const unsigned x3 = xr[i];
;         const float a0 = cb[0] + cw[0][0] * bflo(x0) + cw[1][0] * bflo(x1) + cw[2][0] * bflo(x2) + cw[3][0] * bflo(x3);
;         const float a1 = cb[1] + cw[0][1] * bfhi(x0) + cw[1][1] * bfhi(x1) + cw[2][1] * bfhi(x2) + cw[3][1] * bfhi(x3);
;         if (t < ntok) xact[(size_t)t * (D / 2)] = pk2(siluf(a0), siluf(a1));
;         x0 = x1; x1 = x2; x2 = x3; }
	v_lshlrev_b32_e32 v34, 16, v46
	v_and_b32_e32 v35, 0xffff0000, v46
	v_pk_fma_f32 v[72:73], v[2:3], v[36:37], v[12:13]
	v_pk_fma_f32 v[72:73], v[4:5], v[30:31], v[72:73]
	v_pk_fma_f32 v[72:73], v[8:9], v[32:33], v[72:73]
	v_pk_fma_f32 v[72:73], v[10:11], v[34:35], v[72:73]
	v_lshlrev_b32_e32 v36, 16, v47
	v_and_b32_e32 v37, 0xffff0000, v47
	v_pk_fma_f32 v[74:75], v[2:3], v[30:31], v[12:13]
	v_pk_fma_f32 v[74:75], v[4:5], v[32:33], v[74:75]
	v_pk_fma_f32 v[74:75], v[8:9], v[34:35], v[74:75]
	v_pk_fma_f32 v[74:75], v[10:11], v[36:37], v[74:75]
	v_pk_mul_f32 v[84:85], v[72:73], v[80:81]
	v_pk_mul_f32 v[86:87], v[74:75], v[80:81]
	v_exp_f32_e32 v84, v84
	v_exp_f32_e32 v85, v85
	v_exp_f32_e32 v86, v86
	v_exp_f32_e32 v87, v87
	v_pk_add_f32 v[84:85], v[84:85], v[82:83]
	v_pk_add_f32 v[86:87], v[86:87], v[82:83]
	v_rcp_f32_e32 v84, v84
	v_rcp_f32_e32 v85, v85
	v_rcp_f32_e32 v86, v86
	v_rcp_f32_e32 v87, v87
	v_pk_mul_f32 v[72:73], v[72:73], v[84:85]
	v_pk_mul_f32 v[74:75], v[74:75], v[86:87]
	v_cvt_pk_bf16_f32 v88, v72, v73
	v_cvt_pk_bf16_f32 v89, v74, v75
	global_store_dword v78, v88, s[6:7]
	global_store_dword v78, v89, s[6:7] offset:2048
	s_add_u32 s6, s6, 0x1000
	s_addc_u32 s7, s7, 0
	s_waitcnt vmcnt(46)
	v_lshlrev_b32_e32 v30, 16, v48
	v_and_b32_e32 v31, 0xffff0000, v48
	v_pk_fma_f32 v[72:73], v[2:3], v[32:33], v[12:13]
	v_pk_fma_f32 v[72:73], v[4:5], v[34:35], v[72:73]
	v_pk_fma_f32 v[72:73], v[8:9], v[36:37], v[72:73]
	v_pk_fma_f32 v[72:73], v[10:11], v[30:31], v[72:73]
	v_lshlrev_b32_e32 v32, 16, v49
	v_and_b32_e32 v33, 0xffff0000, v49
	v_pk_fma_f32 v[74:75], v[2:3], v[34:35], v[12:13]
	v_pk_fma_f32 v[74:75], v[4:5], v[36:37], v[74:75]
	v_pk_fma_f32 v[74:75], v[8:9], v[30:31], v[74:75]
	v_pk_fma_f32 v[74:75], v[10:11], v[32:33], v[74:75]
	v_pk_mul_f32 v[84:85], v[72:73], v[80:81]
	v_pk_mul_f32 v[86:87], v[74:75], v[80:81]
	v_exp_f32_e32 v84, v84
	v_exp_f32_e32 v85, v85
	v_exp_f32_e32 v86, v86
	v_exp_f32_e32 v87, v87
	v_pk_add_f32 v[84:85], v[84:85], v[82:83]
	v_pk_add_f32 v[86:87], v[86:87], v[82:83]
	v_rcp_f32_e32 v84, v84
	v_rcp_f32_e32 v85, v85
	v_rcp_f32_e32 v86, v86
	v_rcp_f32_e32 v87, v87
	v_pk_mul_f32 v[72:73], v[72:73], v[84:85]
	v_pk_mul_f32 v[74:75], v[74:75], v[86:87]
	v_cvt_pk_bf16_f32 v88, v72, v73
	v_cvt_pk_bf16_f32 v89, v74, v75
	global_store_dword v78, v88, s[6:7]
	global_store_dword v78, v89, s[6:7] offset:2048
	s_add_u32 s6, s6, 0x1000
	s_addc_u32 s7, s7, 0
	s_waitcnt vmcnt(46)
	v_lshlrev_b32_e32 v34, 16, v50
	v_and_b32_e32 v35, 0xffff0000, v50
	v_pk_fma_f32 v[72:73], v[2:3], v[36:37], v[12:13]
	v_pk_fma_f32 v[72:73], v[4:5], v[30:31], v[72:73]
	v_pk_fma_f32 v[72:73], v[8:9], v[32:33], v[72:73]
	v_pk_fma_f32 v[72:73], v[10:11], v[34:35], v[72:73]
	v_lshlrev_b32_e32 v36, 16, v51
	v_and_b32_e32 v37, 0xffff0000, v51
	v_pk_fma_f32 v[74:75], v[2:3], v[30:31], v[12:13]
	v_pk_fma_f32 v[74:75], v[4:5], v[32:33], v[74:75]
	v_pk_fma_f32 v[74:75], v[8:9], v[34:35], v[74:75]
	v_pk_fma_f32 v[74:75], v[10:11], v[36:37], v[74:75]
	v_pk_mul_f32 v[84:85], v[72:73], v[80:81]
	v_pk_mul_f32 v[86:87], v[74:75], v[80:81]
	v_exp_f32_e32 v84, v84
	v_exp_f32_e32 v85, v85
	v_exp_f32_e32 v86, v86
	v_exp_f32_e32 v87, v87
	v_pk_add_f32 v[84:85], v[84:85], v[82:83]
	v_pk_add_f32 v[86:87], v[86:87], v[82:83]
	v_rcp_f32_e32 v84, v84
	v_rcp_f32_e32 v85, v85
	v_rcp_f32_e32 v86, v86
	v_rcp_f32_e32 v87, v87
	v_pk_mul_f32 v[72:73], v[72:73], v[84:85]
	v_pk_mul_f32 v[74:75], v[74:75], v[86:87]
	v_cvt_pk_bf16_f32 v88, v72, v73
	v_cvt_pk_bf16_f32 v89, v74, v75
	global_store_dword v78, v88, s[6:7]
	global_store_dword v78, v89, s[6:7] offset:2048
	s_add_u32 s6, s6, 0x1000
	s_addc_u32 s7, s7, 0
	s_waitcnt vmcnt(46)
	v_lshlrev_b32_e32 v30, 16, v52
	v_and_b32_e32 v31, 0xffff0000, v52
	v_pk_fma_f32 v[72:73], v[2:3], v[32:33], v[12:13]
	v_pk_fma_f32 v[72:73], v[4:5], v[34:35], v[72:73]
	v_pk_fma_f32 v[72:73], v[8:9], v[36:37], v[72:73]
	v_pk_fma_f32 v[72:73], v[10:11], v[30:31], v[72:73]
	v_lshlrev_b32_e32 v32, 16, v53
	v_and_b32_e32 v33, 0xffff0000, v53
	v_pk_fma_f32 v[74:75], v[2:3], v[34:35], v[12:13]
	v_pk_fma_f32 v[74:75], v[4:5], v[36:37], v[74:75]
	v_pk_fma_f32 v[74:75], v[8:9], v[30:31], v[74:75]
	v_pk_fma_f32 v[74:75], v[10:11], v[32:33], v[74:75]
	v_pk_mul_f32 v[84:85], v[72:73], v[80:81]
	v_pk_mul_f32 v[86:87], v[74:75], v[80:81]
	v_exp_f32_e32 v84, v84
	v_exp_f32_e32 v85, v85
	v_exp_f32_e32 v86, v86
	v_exp_f32_e32 v87, v87
	v_pk_add_f32 v[84:85], v[84:85], v[82:83]
	v_pk_add_f32 v[86:87], v[86:87], v[82:83]
	v_rcp_f32_e32 v84, v84
	v_rcp_f32_e32 v85, v85
	v_rcp_f32_e32 v86, v86
	v_rcp_f32_e32 v87, v87
	v_pk_mul_f32 v[72:73], v[72:73], v[84:85]
	v_pk_mul_f32 v[74:75], v[74:75], v[86:87]
	v_cvt_pk_bf16_f32 v88, v72, v73
	v_cvt_pk_bf16_f32 v89, v74, v75
	global_store_dword v78, v88, s[6:7]
	global_store_dword v78, v89, s[6:7] offset:2048
	s_add_u32 s6, s6, 0x1000
	s_addc_u32 s7, s7, 0
	s_waitcnt vmcnt(46)
	v_lshlrev_b32_e32 v34, 16, v54
	v_and_b32_e32 v35, 0xffff0000, v54
	v_pk_fma_f32 v[72:73], v[2:3], v[36:37], v[12:13]
	v_pk_fma_f32 v[72:73], v[4:5], v[30:31], v[72:73]
	v_pk_fma_f32 v[72:73], v[8:9], v[32:33], v[72:73]
	v_pk_fma_f32 v[72:73], v[10:11], v[34:35], v[72:73]
	v_lshlrev_b32_e32 v36, 16, v55
	v_and_b32_e32 v37, 0xffff0000, v55
	v_pk_fma_f32 v[74:75], v[2:3], v[30:31], v[12:13]
	v_pk_fma_f32 v[74:75], v[4:5], v[32:33], v[74:75]
	v_pk_fma_f32 v[74:75], v[8:9], v[34:35], v[74:75]
	v_pk_fma_f32 v[74:75], v[10:11], v[36:37], v[74:75]
	v_pk_mul_f32 v[84:85], v[72:73], v[80:81]
	v_pk_mul_f32 v[86:87], v[74:75], v[80:81]
	v_exp_f32_e32 v84, v84
	v_exp_f32_e32 v85, v85
	v_exp_f32_e32 v86, v86
	v_exp_f32_e32 v87, v87
	v_pk_add_f32 v[84:85], v[84:85], v[82:83]
	v_pk_add_f32 v[86:87], v[86:87], v[82:83]
	v_rcp_f32_e32 v84, v84
	v_rcp_f32_e32 v85, v85
	v_rcp_f32_e32 v86, v86
	v_rcp_f32_e32 v87, v87
	v_pk_mul_f32 v[72:73], v[72:73], v[84:85]
	v_pk_mul_f32 v[74:75], v[74:75], v[86:87]
	v_cvt_pk_bf16_f32 v88, v72, v73
	v_cvt_pk_bf16_f32 v89, v74, v75
	global_store_dword v78, v88, s[6:7]
	global_store_dword v78, v89, s[6:7] offset:2048
	s_add_u32 s6, s6, 0x1000
	s_addc_u32 s7, s7, 0
	s_waitcnt vmcnt(30)
; DI unsigned pk2(float lo, float hi) { f32x2 v = {lo, hi}; return __builtin_bit_cast(unsigned, __builtin_convertvector(v, bf16x2v)); }
; DI float bflo(unsigned u) { return __uint_as_float(u << 16); }
; DI float bfhi(unsigned u) { return __uint_as_float(u & 0xffff0000u); }
; DI float siluf(float x) { return x * __builtin_amdgcn_rcpf(1.f + __expf(-x)); }
; DI void precompute_item(const Params& p, int item, ldsp lds, int tid_) {
;     ...
;     for (int tb = 0; tb < nb; ++tb) {
;       unsigned xr[16];
; #pragma unroll
;       for (int i = 0; i < 16; ++i) { const int t = tb * 16 + i; xr[i] = (t < ntok) ? *(const unsigned*)(proj + (size_t)(r0 + t) * NINP + C_XBC + ch) : 0u; }
; #pragma unroll
;       for (int i = 0; i < 16; ++i) { const int t = tb * 16 + i; const unsigned x3 = xr[i];
;         const float a0 = cb[0] + cw[0][0] * bflo(x0) + cw[1][0] * bflo(x1) + cw[2][0] * bflo(x2) + cw[3][0] * bflo(x3);
;         const float a1 = cb[1] + cw[0][1] * bfhi(x0) + cw[1][1] * bfhi(x1) + cw[2][1] * bfhi(x2) + cw[3][1] * bfhi(x3);
;         if (t < ntok) xact[(size_t)t * (D / 2)] = pk2(siluf(a0), siluf(a1));
;         x0 = x1; x1 = x2; x2 = x3; }
	v_lshlrev_b32_e32 v30, 16, v56
	v_and_b32_e32 v31, 0xffff0000, v56
	v_pk_fma_f32 v[72:73], v[2:3], v[32:33], v[12:13]
	v_pk_fma_f32 v[72:73], v[4:5], v[34:35], v[72:73]
	v_pk_fma_f32 v[72:73], v[8:9], v[36:37], v[72:73]
	v_pk_fma_f32 v[72:73], v[10:11], v[30:31], v[72:73]
	v_lshlrev_b32_e32 v32, 16, v57
	v_and_b32_e32 v33, 0xffff0000, v57
	v_pk_fma_f32 v[74:75], v[2:3], v[34:35], v[12:13]
	v_pk_fma_f32 v[74:75], v[4:5], v[36:37], v[74:75]
	v_pk_fma_f32 v[74:75], v[8:9], v[30:31], v[74:75]
	v_pk_fma_f32 v[74:75], v[10:11], v[32:33], v[74:75]
	v_pk_mul_f32 v[84:85], v[72:73], v[80:81]
	v_pk_mul_f32 v[86:87], v[74:75], v[80:81]
	v_exp_f32_e32 v84, v84
	v_exp_f32_e32 v85, v85
	v_exp_f32_e32 v86, v86
	v_exp_f32_e32 v87, v87
	v_pk_add_f32 v[84:85], v[84:85], v[82:83]
	v_pk_add_f32 v[86:87], v[86:87], v[82:83]
	v_rcp_f32_e32 v84, v84
	v_rcp_f32_e32 v85, v85
	v_rcp_f32_e32 v86, v86
	v_rcp_f32_e32 v87, v87
	v_pk_mul_f32 v[72:73], v[72:73], v[84:85]
	v_pk_mul_f32 v[74:75], v[74:75], v[86:87]
	v_cvt_pk_bf16_f32 v88, v72, v73
	v_cvt_pk_bf16_f32 v89, v74, v75
	global_store_dword v78, v88, s[6:7]
	global_store_dword v78, v89, s[6:7] offset:2048
	s_add_u32 s6, s6, 0x1000
	s_addc_u32 s7, s7, 0
	s_waitcnt vmcnt(30)
	v_lshlrev_b32_e32 v34, 16, v58
	v_and_b32_e32 v35, 0xffff0000, v58
	v_pk_fma_f32 v[72:73], v[2:3], v[36:37], v[12:13]
	v_pk_fma_f32 v[72:73], v[4:5], v[30:31], v[72:73]
	v_pk_fma_f32 v[72:73], v[8:9], v[32:33], v[72:73]
	v_pk_fma_f32 v[72:73], v[10:11], v[34:35], v[72:73]
	v_lshlrev_b32_e32 v36, 16, v59
	v_and_b32_e32 v37, 0xffff0000, v59
	v_pk_fma_f32 v[74:75], v[2:3], v[30:31], v[12:13]
	v_pk_fma_f32 v[74:75], v[4:5], v[32:33], v[74:75]
	v_pk_fma_f32 v[74:75], v[8:9], v[34:35], v[74:75]
	v_pk_fma_f32 v[74:75], v[10:11], v[36:37], v[74:75]
	v_pk_mul_f32 v[84:85], v[72:73], v[80:81]
	v_pk_mul_f32 v[86:87], v[74:75], v[80:81]
	v_exp_f32_e32 v84, v84
	v_exp_f32_e32 v85, v85
	v_exp_f32_e32 v86, v86
	v_exp_f32_e32 v87, v87
	v_pk_add_f32 v[84:85], v[84:85], v[82:83]
	v_pk_add_f32 v[86:87], v[86:87], v[82:83]
	v_rcp_f32_e32 v84, v84
	v_rcp_f32_e32 v85, v85
	v_rcp_f32_e32 v86, v86
	v_rcp_f32_e32 v87, v87
	v_pk_mul_f32 v[72:73], v[72:73], v[84:85]
	v_pk_mul_f32 v[74:75], v[74:75], v[86:87]
	v_cvt_pk_bf16_f32 v88, v72, v73
	v_cvt_pk_bf16_f32 v89, v74, v75
	global_store_dword v78, v88, s[6:7]
	global_store_dword v78, v89, s[6:7] offset:2048
	s_add_u32 s6, s6, 0x1000
	s_addc_u32 s7, s7, 0
	s_waitcnt vmcnt(30)
	v_lshlrev_b32_e32 v30, 16, v60
	v_and_b32_e32 v31, 0xffff0000, v60
	v_pk_fma_f32 v[72:73], v[2:3], v[32:33], v[12:13]
	v_pk_fma_f32 v[72:73], v[4:5], v[34:35], v[72:73]
	v_pk_fma_f32 v[72:73], v[8:9], v[36:37], v[72:73]
	v_pk_fma_f32 v[72:73], v[10:11], v[30:31], v[72:73]
	v_lshlrev_b32_e32 v32, 16, v61
	v_and_b32_e32 v33, 0xffff0000, v61
	v_pk_fma_f32 v[74:75], v[2:3], v[34:35], v[12:13]
	v_pk_fma_f32 v[74:75], v[4:5], v[36:37], v[74:75]
	v_pk_fma_f32 v[74:75], v[8:9], v[30:31], v[74:75]
	v_pk_fma_f32 v[74:75], v[10:11], v[32:33], v[74:75]
	v_pk_mul_f32 v[84:85], v[72:73], v[80:81]
	v_pk_mul_f32 v[86:87], v[74:75], v[80:81]
	v_exp_f32_e32 v84, v84
	v_exp_f32_e32 v85, v85
	v_exp_f32_e32 v86, v86
	v_exp_f32_e32 v87, v87
	v_pk_add_f32 v[84:85], v[84:85], v[82:83]
	v_pk_add_f32 v[86:87], v[86:87], v[82:83]
	v_rcp_f32_e32 v84, v84
	v_rcp_f32_e32 v85, v85
	v_rcp_f32_e32 v86, v86
	v_rcp_f32_e32 v87, v87
	v_pk_mul_f32 v[72:73], v[72:73], v[84:85]
	v_pk_mul_f32 v[74:75], v[74:75], v[86:87]
	v_cvt_pk_bf16_f32 v88, v72, v73
	v_cvt_pk_bf16_f32 v89, v74, v75
	global_store_dword v78, v88, s[6:7]
	global_store_dword v78, v89, s[6:7] offset:2048
	s_add_u32 s6, s6, 0x1000
	s_addc_u32 s7, s7, 0
	s_waitcnt vmcnt(30)
	v_lshlrev_b32_e32 v34, 16, v62
	v_and_b32_e32 v35, 0xffff0000, v62
	v_pk_fma_f32 v[72:73], v[2:3], v[36:37], v[12:13]
	v_pk_fma_f32 v[72:73], v[4:5], v[30:31], v[72:73]
	v_pk_fma_f32 v[72:73], v[8:9], v[32:33], v[72:73]
	v_pk_fma_f32 v[72:73], v[10:11], v[34:35], v[72:73]
	v_lshlrev_b32_e32 v36, 16, v63
	v_and_b32_e32 v37, 0xffff0000, v63
	v_pk_fma_f32 v[74:75], v[2:3], v[30:31], v[12:13]
	v_pk_fma_f32 v[74:75], v[4:5], v[32:33], v[74:75]
	v_pk_fma_f32 v[74:75], v[8:9], v[34:35], v[74:75]
	v_pk_fma_f32 v[74:75], v[10:11], v[36:37], v[74:75]
	v_pk_mul_f32 v[84:85], v[72:73], v[80:81]
	v_pk_mul_f32 v[86:87], v[74:75], v[80:81]
	v_exp_f32_e32 v84, v84
	v_exp_f32_e32 v85, v85
	v_exp_f32_e32 v86, v86
	v_exp_f32_e32 v87, v87
	v_pk_add_f32 v[84:85], v[84:85], v[82:83]
	v_pk_add_f32 v[86:87], v[86:87], v[82:83]
	v_rcp_f32_e32 v84, v84
	v_rcp_f32_e32 v85, v85
	v_rcp_f32_e32 v86, v86
	v_rcp_f32_e32 v87, v87
	v_pk_mul_f32 v[72:73], v[72:73], v[84:85]
	v_pk_mul_f32 v[74:75], v[74:75], v[86:87]
	v_cvt_pk_bf16_f32 v88, v72, v73
	v_cvt_pk_bf16_f32 v89, v74, v75
	global_store_dword v78, v88, s[6:7]
	global_store_dword v78, v89, s[6:7] offset:2048
	s_add_u32 s6, s6, 0x1000
	s_addc_u32 s7, s7, 0
	s_waitcnt vmcnt(30)
	v_lshlrev_b32_e32 v30, 16, v64
	v_and_b32_e32 v31, 0xffff0000, v64
	v_pk_fma_f32 v[72:73], v[2:3], v[32:33], v[12:13]
	v_pk_fma_f32 v[72:73], v[4:5], v[34:35], v[72:73]
	v_pk_fma_f32 v[72:73], v[8:9], v[36:37], v[72:73]
	v_pk_fma_f32 v[72:73], v[10:11], v[30:31], v[72:73]
	v_lshlrev_b32_e32 v32, 16, v65
	v_and_b32_e32 v33, 0xffff0000, v65
	v_pk_fma_f32 v[74:75], v[2:3], v[34:35], v[12:13]
	v_pk_fma_f32 v[74:75], v[4:5], v[36:37], v[74:75]
	v_pk_fma_f32 v[74:75], v[8:9], v[30:31], v[74:75]
	v_pk_fma_f32 v[74:75], v[10:11], v[32:33], v[74:75]
	v_pk_mul_f32 v[84:85], v[72:73], v[80:81]
	v_pk_mul_f32 v[86:87], v[74:75], v[80:81]
	v_exp_f32_e32 v84, v84
	v_exp_f32_e32 v85, v85
	v_exp_f32_e32 v86, v86
	v_exp_f32_e32 v87, v87
	v_pk_add_f32 v[84:85], v[84:85], v[82:83]
	v_pk_add_f32 v[86:87], v[86:87], v[82:83]
	v_rcp_f32_e32 v84, v84
	v_rcp_f32_e32 v85, v85
	v_rcp_f32_e32 v86, v86
	v_rcp_f32_e32 v87, v87
	v_pk_mul_f32 v[72:73], v[72:73], v[84:85]
	v_pk_mul_f32 v[74:75], v[74:75], v[86:87]
	v_cvt_pk_bf16_f32 v88, v72, v73
	v_cvt_pk_bf16_f32 v89, v74, v75
	global_store_dword v78, v88, s[6:7]
	global_store_dword v78, v89, s[6:7] offset:2048
	s_add_u32 s6, s6, 0x1000
	s_addc_u32 s7, s7, 0
	s_waitcnt vmcnt(30)
; DI unsigned pk2(float lo, float hi) { f32x2 v = {lo, hi}; return __builtin_bit_cast(unsigned, __builtin_convertvector(v, bf16x2v)); }
; DI float bflo(unsigned u) { return __uint_as_float(u << 16); }
; DI float bfhi(unsigned u) { return __uint_as_float(u & 0xffff0000u); }
; DI float siluf(float x) { return x * __builtin_amdgcn_rcpf(1.f + __expf(-x)); }
; DI void precompute_item(const Params& p, int item, ldsp lds, int tid_) {
;     ...
;       for (int i = 0; i < 16; ++i) { const int t = tb * 16 + i; const unsigned x3 = xr[i];
;         const float a0 = cb[0] + cw[0][0] * bflo(x0) + cw[1][0] * bflo(x1) + cw[2][0] * bflo(x2) + cw[3][0] * bflo(x3);
;         const float a1 = cb[1] + cw[0][1] * bfhi(x0) + cw[1][1] * bfhi(x1) + cw[2][1] * bfhi(x2) + cw[3][1] * bfhi(x3);
;         if (t < ntok) xact[(size_t)t * (D / 2)] = pk2(siluf(a0), siluf(a1));
;         x0 = x1; x1 = x2; x2 = x3; }
	v_lshlrev_b32_e32 v34, 16, v66
	v_and_b32_e32 v35, 0xffff0000, v66
	v_pk_fma_f32 v[72:73], v[2:3], v[36:37], v[12:13]
	v_pk_fma_f32 v[72:73], v[4:5], v[30:31], v[72:73]
	v_pk_fma_f32 v[72:73], v[8:9], v[32:33], v[72:73]
	v_pk_fma_f32 v[72:73], v[10:11], v[34:35], v[72:73]
	v_lshlrev_b32_e32 v36, 16, v67
	v_and_b32_e32 v37, 0xffff0000, v67
	v_pk_fma_f32 v[74:75], v[2:3], v[30:31], v[12:13]
	v_pk_fma_f32 v[74:75], v[4:5], v[32:33], v[74:75]
	v_pk_fma_f32 v[74:75], v[8:9], v[34:35], v[74:75]
	v_pk_fma_f32 v[74:75], v[10:11], v[36:37], v[74:75]
	v_pk_mul_f32 v[84:85], v[72:73], v[80:81]
	v_pk_mul_f32 v[86:87], v[74:75], v[80:81]
	v_exp_f32_e32 v84, v84
	v_exp_f32_e32 v85, v85
	v_exp_f32_e32 v86, v86
	v_exp_f32_e32 v87, v87
	v_pk_add_f32 v[84:85], v[84:85], v[82:83]
	v_pk_add_f32 v[86:87], v[86:87], v[82:83]
	v_rcp_f32_e32 v84, v84
	v_rcp_f32_e32 v85, v85
	v_rcp_f32_e32 v86, v86
	v_rcp_f32_e32 v87, v87
	v_pk_mul_f32 v[72:73], v[72:73], v[84:85]
	v_pk_mul_f32 v[74:75], v[74:75], v[86:87]
	v_cvt_pk_bf16_f32 v88, v72, v73
	v_cvt_pk_bf16_f32 v89, v74, v75
	global_store_dword v78, v88, s[6:7]
	global_store_dword v78, v89, s[6:7] offset:2048
	s_add_u32 s6, s6, 0x1000
	s_addc_u32 s7, s7, 0
	s_waitcnt vmcnt(30)
	v_lshlrev_b32_e32 v30, 16, v68
	v_and_b32_e32 v31, 0xffff0000, v68
	v_pk_fma_f32 v[72:73], v[2:3], v[32:33], v[12:13]
	v_pk_fma_f32 v[72:73], v[4:5], v[34:35], v[72:73]
	v_pk_fma_f32 v[72:73], v[8:9], v[36:37], v[72:73]
	v_pk_fma_f32 v[72:73], v[10:11], v[30:31], v[72:73]
	v_lshlrev_b32_e32 v32, 16, v69
	v_and_b32_e32 v33, 0xffff0000, v69
	v_pk_fma_f32 v[74:75], v[2:3], v[34:35], v[12:13]
	v_pk_fma_f32 v[74:75], v[4:5], v[36:37], v[74:75]
	v_pk_fma_f32 v[74:75], v[8:9], v[30:31], v[74:75]
	v_pk_fma_f32 v[74:75], v[10:11], v[32:33], v[74:75]
	v_pk_mul_f32 v[84:85], v[72:73], v[80:81]
	v_pk_mul_f32 v[86:87], v[74:75], v[80:81]
	v_exp_f32_e32 v84, v84
	v_exp_f32_e32 v85, v85
	v_exp_f32_e32 v86, v86
	v_exp_f32_e32 v87, v87
	v_pk_add_f32 v[84:85], v[84:85], v[82:83]
	v_pk_add_f32 v[86:87], v[86:87], v[82:83]
	v_rcp_f32_e32 v84, v84
	v_rcp_f32_e32 v85, v85
	v_rcp_f32_e32 v86, v86
	v_rcp_f32_e32 v87, v87
	v_pk_mul_f32 v[72:73], v[72:73], v[84:85]
	v_pk_mul_f32 v[74:75], v[74:75], v[86:87]
	v_cvt_pk_bf16_f32 v88, v72, v73
	v_cvt_pk_bf16_f32 v89, v74, v75
	global_store_dword v78, v88, s[6:7]
	global_store_dword v78, v89, s[6:7] offset:2048
	s_add_u32 s6, s6, 0x1000
	s_addc_u32 s7, s7, 0
	s_waitcnt vmcnt(30)
	v_lshlrev_b32_e32 v34, 16, v70
	v_and_b32_e32 v35, 0xffff0000, v70
	v_pk_fma_f32 v[72:73], v[2:3], v[36:37], v[12:13]
	v_pk_fma_f32 v[72:73], v[4:5], v[30:31], v[72:73]
	v_pk_fma_f32 v[72:73], v[8:9], v[32:33], v[72:73]
	v_pk_fma_f32 v[72:73], v[10:11], v[34:35], v[72:73]
	v_lshlrev_b32_e32 v36, 16, v71
	v_and_b32_e32 v37, 0xffff0000, v71
	v_pk_fma_f32 v[74:75], v[2:3], v[30:31], v[12:13]
	v_pk_fma_f32 v[74:75], v[4:5], v[32:33], v[74:75]
	v_pk_fma_f32 v[74:75], v[8:9], v[34:35], v[74:75]
	v_pk_fma_f32 v[74:75], v[10:11], v[36:37], v[74:75]
	v_pk_mul_f32 v[84:85], v[72:73], v[80:81]
	v_pk_mul_f32 v[86:87], v[74:75], v[80:81]
	v_exp_f32_e32 v84, v84
	v_exp_f32_e32 v85, v85
	v_exp_f32_e32 v86, v86
	v_exp_f32_e32 v87, v87
	v_pk_add_f32 v[84:85], v[84:85], v[82:83]
	v_pk_add_f32 v[86:87], v[86:87], v[82:83]
	v_rcp_f32_e32 v84, v84
	v_rcp_f32_e32 v85, v85
	v_rcp_f32_e32 v86, v86
	v_rcp_f32_e32 v87, v87
	v_pk_mul_f32 v[72:73], v[72:73], v[84:85]
	v_pk_mul_f32 v[74:75], v[74:75], v[86:87]
	v_cvt_pk_bf16_f32 v88, v72, v73
	v_cvt_pk_bf16_f32 v89, v74, v75
	global_store_dword v78, v88, s[6:7]
	global_store_dword v78, v89, s[6:7] offset:2048
	s_add_u32 s6, s6, 0x1000
	s_addc_u32 s7, s7, 0
	s_branch .Lp13c_done
; DI unsigned pk2(float lo, float hi) { f32x2 v = {lo, hi}; return __builtin_bit_cast(unsigned, __builtin_convertvector(v, bf16x2v)); }
; DI float bf2f(bf16_t b) { return __uint_as_float(((unsigned)b) << 16); }
; DI float bflo(unsigned u) { return __uint_as_float(u << 16); }
; DI float bfhi(unsigned u) { return __uint_as_float(u & 0xffff0000u); }
; DI float siluf(float x) { return x * __builtin_amdgcn_rcpf(1.f + __expf(-x)); }
; DI float softplusf(float x) { return fmaxf(x, 0.f) + __logf(1.f + __expf(-fabsf(x))); }
; DI void precompute_item(const Params& p, int item, ldsp lds, int tid_) {
;     ...
;     for (int tb = 0; tb < nb; ++tb) {
;       unsigned xr[16];
; #pragma unroll
;       for (int i = 0; i < 16; ++i) { const int t = tb * 16 + i; xr[i] = (t < ntok) ? *(const unsigned*)(proj + (size_t)(r0 + t) * NINP + C_XBC + ch) : 0u; }
; #pragma unroll
;       for (int i = 0; i < 16; ++i) { const int t = tb * 16 + i; const unsigned x3 = xr[i];
;         const float a0 = cb[0] + cw[0][0] * bflo(x0) + cw[1][0] * bflo(x1) + cw[2][0] * bflo(x2) + cw[3][0] * bflo(x3);
;         const float a1 = cb[1] + cw[0][1] * bfhi(x0) + cw[1][1] * bfhi(x1) + cw[2][1] * bfhi(x2) + cw[3][1] * bfhi(x3);
;         if (t < ntok) xact[(size_t)t * (D / 2)] = pk2(siluf(a0), siluf(a1));
;         x0 = x1; x1 = x2; x2 = x3; }
;     ...
;   { const float dtb = p.in[16][wid], aneg = -__expf(p.in[17][wid]);
;     const float raw = (lane < ntok) ? bf2f(proj[(size_t)(r0 + lane) * NINP + C_DT + wid]) : 0.f;
;     const float dtv = (lane < ntok) ? softplusf(raw + dtb) : 0.f;
.Lp13c_small:
	global_load_dword v40, v78, s[4:5]
	s_add_u32 s4, s4, 0x1a00
	s_addc_u32 s5, s5, 0
	global_load_dword v41, v78, s[4:5]
	s_add_u32 s4, s4, 0x1a00
	s_addc_u32 s5, s5, 0
	global_load_dword v42, v78, s[4:5]
	s_add_u32 s4, s4, 0x1a00
	s_addc_u32 s5, s5, 0
	global_load_dword v43, v78, s[4:5]
	s_add_u32 s4, s4, 0x1a00
	s_addc_u32 s5, s5, 0
	s_waitcnt vmcnt(2)
	v_lshlrev_b32_e32 v32, 16, v22
	v_and_b32_e32 v33, 0xffff0000, v22
	v_lshlrev_b32_e32 v34, 16, v21
	v_and_b32_e32 v35, 0xffff0000, v21
	v_lshlrev_b32_e32 v36, 16, v19
	v_and_b32_e32 v37, 0xffff0000, v19
	v_lshlrev_b32_e32 v30, 16, v40
	v_and_b32_e32 v31, 0xffff0000, v40
	v_pk_fma_f32 v[72:73], v[2:3], v[32:33], v[12:13]
	v_pk_fma_f32 v[72:73], v[4:5], v[34:35], v[72:73]
	v_pk_fma_f32 v[72:73], v[8:9], v[36:37], v[72:73]
	v_pk_fma_f32 v[72:73], v[10:11], v[30:31], v[72:73]
	v_lshlrev_b32_e32 v32, 16, v41
	v_and_b32_e32 v33, 0xffff0000, v41
	v_pk_fma_f32 v[74:75], v[2:3], v[34:35], v[12:13]
	v_pk_fma_f32 v[74:75], v[4:5], v[36:37], v[74:75]
	v_pk_fma_f32 v[74:75], v[8:9], v[30:31], v[74:75]
	v_pk_fma_f32 v[74:75], v[10:11], v[32:33], v[74:75]
	v_pk_mul_f32 v[84:85], v[72:73], v[80:81]
	v_pk_mul_f32 v[86:87], v[74:75], v[80:81]
	v_exp_f32_e32 v84, v84
	v_exp_f32_e32 v85, v85
	v_exp_f32_e32 v86, v86
	v_exp_f32_e32 v87, v87
	v_pk_add_f32 v[84:85], v[84:85], v[82:83]
	v_pk_add_f32 v[86:87], v[86:87], v[82:83]
	v_rcp_f32_e32 v84, v84
	v_rcp_f32_e32 v85, v85
	v_rcp_f32_e32 v86, v86
	v_rcp_f32_e32 v87, v87
	v_pk_mul_f32 v[72:73], v[72:73], v[84:85]
	v_pk_mul_f32 v[74:75], v[74:75], v[86:87]
	v_cvt_pk_bf16_f32 v88, v72, v73
	v_cvt_pk_bf16_f32 v89, v74, v75
	global_store_dword v78, v88, s[6:7]
	global_store_dword v78, v89, s[6:7] offset:2048
	s_add_u32 s6, s6, 0x1000
	s_addc_u32 s7, s7, 0
	s_waitcnt vmcnt(2)
	v_lshlrev_b32_e32 v34, 16, v42
	v_and_b32_e32 v35, 0xffff0000, v42
	v_pk_fma_f32 v[72:73], v[2:3], v[36:37], v[12:13]
	v_pk_fma_f32 v[72:73], v[4:5], v[30:31], v[72:73]
	v_pk_fma_f32 v[72:73], v[8:9], v[32:33], v[72:73]
	v_pk_fma_f32 v[72:73], v[10:11], v[34:35], v[72:73]
	v_lshlrev_b32_e32 v36, 16, v43
	v_and_b32_e32 v37, 0xffff0000, v43
	v_pk_fma_f32 v[74:75], v[2:3], v[30:31], v[12:13]
	v_pk_fma_f32 v[74:75], v[4:5], v[32:33], v[74:75]
	v_pk_fma_f32 v[74:75], v[8:9], v[34:35], v[74:75]
	v_pk_fma_f32 v[74:75], v[10:11], v[36:37], v[74:75]
	v_pk_mul_f32 v[84:85], v[72:73], v[80:81]
	v_pk_mul_f32 v[86:87], v[74:75], v[80:81]
	v_exp_f32_e32 v84, v84
	v_exp_f32_e32 v85, v85
	v_exp_f32_e32 v86, v86
	v_exp_f32_e32 v87, v87
	v_pk_add_f32 v[84:85], v[84:85], v[82:83]
	v_pk_add_f32 v[86:87], v[86:87], v[82:83]
	v_rcp_f32_e32 v84, v84
	v_rcp_f32_e32 v85, v85
	v_rcp_f32_e32 v86, v86
	v_rcp_f32_e32 v87, v87
	v_pk_mul_f32 v[72:73], v[72:73], v[84:85]
	v_pk_mul_f32 v[74:75], v[74:75], v[86:87]
	v_cvt_pk_bf16_f32 v88, v72, v73
	v_cvt_pk_bf16_f32 v89, v74, v75
	global_store_dword v78, v88, s[6:7]
	global_store_dword v78, v89, s[6:7] offset:2048
	s_add_u32 s6, s6, 0x1000
	s_addc_u32 s7, s7, 0
.Lp13c_done:
.LBB0_438:
	s_ashr_i32 s78, s0, 6
	s_ashr_i32 s79, s78, 31
	s_lshl_b64 s[6:7], s[78:79], 2
	s_add_u32 s4, s50, s6
	s_addc_u32 s5, s51, s7
	global_load_dword v1, v7, s[4:5]
	v_and_b32_e32 v20, 63, v26
	v_cmp_gt_u32_e64 s[4:5], s3, v20
	v_mov_b32_e32 v2, 0
	v_add_u32_e32 v0, s76, v20
	s_and_saveexec_b64 s[8:9], s[4:5]
	s_cbranch_execz .LBB0_440
	v_mov_b64_e32 v[2:3], s[62:63]
	v_mad_i64_i32 v[2:3], s[10:11], v0, s85, v[2:3]
	v_lshl_add_u64 v[2:3], s[78:79], 1, v[2:3]
	v_add_co_u32_e32 v2, vcc, 0x1000, v2
	s_add_u32 s6, s48, s6
	s_nop 0
	v_addc_co_u32_e32 v3, vcc, 0, v3, vcc
	s_addc_u32 s7, s49, s7
	global_load_ushort v2, v[2:3], off offset:2080
	s_nop 0
	global_load_dword v3, v7, s[6:7]
	s_waitcnt vmcnt(1)
	v_lshlrev_b32_e32 v2, 16, v2
	s_waitcnt vmcnt(0)
	v_add_f32_e32 v2, v3, v2
	v_mul_f32_e64 v3, |v2|, s86
	v_exp_f32_e32 v3, v3
	v_max_f32_e32 v2, 0, v2
	v_add_f32_e32 v3, 1.0, v3
	v_cmp_gt_f32_e32 vcc, s87, v3
	s_nop 1
	v_cndmask_b32_e64 v4, 0, 32, vcc
	v_ldexp_f32 v3, v3, v4
	v_log_f32_e32 v3, v3
	s_nop 0
	v_mul_f32_e32 v4, 0x3f317217, v3
	v_fma_f32 v4, v3, s88, -v4
	v_fmac_f32_e32 v4, 0x3377d1cf, v3
	v_fmac_f32_e32 v4, 0x3f317217, v3
	v_cmp_lt_f32_e64 s[6:7], |v3|, s89
	s_nop 1
	v_cndmask_b32_e64 v3, v3, v4, s[6:7]
	v_cndmask_b32_e32 v4, 0, v25, vcc
	v_sub_f32_e32 v3, v3, v4
	v_add_f32_e32 v2, v2, v3
